# v69 (no K-loop setprio flips) + redundant post-barrier lgkmcnt waits removed + LDS-DMA addresses in saddr form (no 64-bit VALU adds in K-loop load segments)
# speedup vs baseline: 1.0111x; 1.0034x over previous
.LBB0_184:
	s_add_i32 s90, s58, 2
	s_add_u32 s56, s54, 0x100
	s_addc_u32 s57, s55, 0
	s_add_i32 s91, 0, 0x10000
	s_cmp_eq_u32 s46, s58
	s_cselect_b32 s61, s18, s57
	s_cselect_b32 s60, s19, s56
	v_add_u32_e32 v140, s91, v143
	s_cselect_b32 s59, s22, s89
	s_cselect_b32 s58, s23, s47
	s_add_i32 vcc_lo, 0, 0x14000
	ds_read_b128 v[146:149], v140
	ds_read_b128 v[150:153], v140 offset:1024
	ds_read_b128 v[154:157], v140 offset:2048
	ds_read_b128 v[158:161], v140 offset:3072
	v_add_u32_e32 v140, vcc_lo, v143
	ds_read_b128 v[162:165], v140
	ds_read_b128 v[176:179], v140 offset:1024
	ds_read_b128 v[180:183], v140 offset:2048
	ds_read_b128 v[184:187], v140 offset:3072
	s_add_i32 m0, s39, 0xc000
	ds_read_b128 v[188:191], v144
	ds_read_b128 v[192:195], v144 offset:1024
	ds_read_b128 v[196:199], v144 offset:2048
	ds_read_b128 v[200:203], v144 offset:3072
	ds_read_b128 v[204:207], v144 offset:4096
	ds_read_b128 v[208:211], v144 offset:5120
	ds_read_b128 v[212:215], v144 offset:6144
	ds_read_b128 v[220:223], v144 offset:7168
	global_load_lds_dwordx4 v136, s[54:55]
	s_add_i32 m0, s39, 0xe000
	s_nop 0
	global_load_lds_dwordx4 v138, s[54:55]
	s_waitcnt vmcnt(8)
	s_waitcnt lgkmcnt(0)
	s_barrier
	v_mfma_f32_16x16x32_bf16 v[126:129], v[146:149], v[188:191], v[126:129]
	v_mfma_f32_16x16x32_bf16 v[122:125], v[154:157], v[188:191], v[122:125]
	v_mfma_f32_16x16x32_bf16 v[118:121], v[146:149], v[196:199], v[118:121]
	v_mfma_f32_16x16x32_bf16 v[110:113], v[154:157], v[196:199], v[110:113]
	v_mfma_f32_16x16x32_bf16 v[102:105], v[146:149], v[204:207], v[102:105]
	v_mfma_f32_16x16x32_bf16 v[94:97], v[154:157], v[204:207], v[94:97]
	v_mfma_f32_16x16x32_bf16 v[86:89], v[146:149], v[212:215], v[86:89]
	v_mfma_f32_16x16x32_bf16 v[78:81], v[154:157], v[212:215], v[78:81]
	v_mfma_f32_16x16x32_bf16 v[126:129], v[150:153], v[192:195], v[126:129]
	v_mfma_f32_16x16x32_bf16 v[122:125], v[158:161], v[192:195], v[122:125]
	v_mfma_f32_16x16x32_bf16 v[118:121], v[150:153], v[200:203], v[118:121]
	v_mfma_f32_16x16x32_bf16 v[110:113], v[158:161], v[200:203], v[110:113]
	v_mfma_f32_16x16x32_bf16 v[102:105], v[150:153], v[208:211], v[102:105]
	v_mfma_f32_16x16x32_bf16 v[94:97], v[158:161], v[208:211], v[94:97]
	v_mfma_f32_16x16x32_bf16 v[86:89], v[150:153], v[220:223], v[86:89]
	v_mfma_f32_16x16x32_bf16 v[78:81], v[158:161], v[220:223], v[78:81]
	v_mfma_f32_16x16x32_bf16 v[114:117], v[162:165], v[188:191], v[114:117]
	v_mfma_f32_16x16x32_bf16 v[106:109], v[180:183], v[188:191], v[106:109]
	v_mfma_f32_16x16x32_bf16 v[98:101], v[162:165], v[196:199], v[98:101]
	v_mfma_f32_16x16x32_bf16 v[90:93], v[180:183], v[196:199], v[90:93]
	v_mfma_f32_16x16x32_bf16 v[82:85], v[162:165], v[204:207], v[82:85]
	v_mfma_f32_16x16x32_bf16 v[74:77], v[180:183], v[204:207], v[74:77]
	v_mfma_f32_16x16x32_bf16 v[70:73], v[162:165], v[212:215], v[70:73]
	v_mfma_f32_16x16x32_bf16 v[66:69], v[180:183], v[212:215], v[66:69]
	v_mfma_f32_16x16x32_bf16 v[114:117], v[176:179], v[192:195], v[114:117]
	v_mfma_f32_16x16x32_bf16 v[106:109], v[184:187], v[192:195], v[106:109]
	v_mfma_f32_16x16x32_bf16 v[98:101], v[176:179], v[200:203], v[98:101]
	v_mfma_f32_16x16x32_bf16 v[90:93], v[184:187], v[200:203], v[90:93]
	v_mfma_f32_16x16x32_bf16 v[82:85], v[176:179], v[208:211], v[82:85]
	v_mfma_f32_16x16x32_bf16 v[74:77], v[184:187], v[208:211], v[74:77]
	v_mfma_f32_16x16x32_bf16 v[70:73], v[176:179], v[220:223], v[70:73]
	v_mfma_f32_16x16x32_bf16 v[66:69], v[184:187], v[220:223], v[66:69]
	s_barrier
	s_add_u32 s98, s58, s28
	s_addc_u32 s99, s59, s29
	s_add_u32 s100, s60, s28
	s_addc_u32 s101, s61, s29
	s_add_i32 s54, s91, s38
	s_mov_b32 m0, s54
	ds_read_b128 v[188:191], v144 offset:16384
	ds_read_b128 v[192:195], v144 offset:17408
	ds_read_b128 v[196:199], v144 offset:18432
	ds_read_b128 v[200:203], v144 offset:19456
	ds_read_b128 v[204:207], v144 offset:20480
	ds_read_b128 v[208:211], v144 offset:21504
	ds_read_b128 v[212:215], v144 offset:22528
	ds_read_b128 v[220:223], v144 offset:23552
	global_load_lds_dwordx4 v32, s[58:59]
	s_add_i32 m0, s54, 0x2000
	s_add_u32 s54, s58, 0xb0000
	s_addc_u32 s55, s59, 0
	s_add_i32 s91, vcc_lo, s38
	global_load_lds_dwordx4 v134, s[58:59]
	s_mov_b32 m0, s91
	s_nop 0
	global_load_lds_dwordx4 v32, s[54:55]
	s_add_i32 m0, s91, 0x2000
	s_nop 0
	global_load_lds_dwordx4 v134, s[54:55]
	s_mov_b32 m0, s39
	s_nop 0
	global_load_lds_dwordx4 v130, s[60:61]
	s_mov_b32 m0, s62
	s_nop 0
	global_load_lds_dwordx4 v132, s[60:61]
	s_waitcnt vmcnt(8)
	s_waitcnt lgkmcnt(0)
	s_barrier
	v_mfma_f32_16x16x32_bf16 v[62:65], v[146:149], v[188:191], v[62:65]
	v_mfma_f32_16x16x32_bf16 v[58:61], v[154:157], v[188:191], v[58:61]
	v_mfma_f32_16x16x32_bf16 v[54:57], v[146:149], v[196:199], v[54:57]
	v_mfma_f32_16x16x32_bf16 v[46:49], v[154:157], v[196:199], v[46:49]
	v_mfma_f32_16x16x32_bf16 v[38:41], v[146:149], v[204:207], v[38:41]
	v_mfma_f32_16x16x32_bf16 v[28:31], v[154:157], v[204:207], v[28:31]
	v_mfma_f32_16x16x32_bf16 v[20:23], v[146:149], v[212:215], v[20:23]
	v_mfma_f32_16x16x32_bf16 v[12:15], v[154:157], v[212:215], v[12:15]
	v_mfma_f32_16x16x32_bf16 v[62:65], v[150:153], v[192:195], v[62:65]
	v_mfma_f32_16x16x32_bf16 v[58:61], v[158:161], v[192:195], v[58:61]
	v_mfma_f32_16x16x32_bf16 v[54:57], v[150:153], v[200:203], v[54:57]
	v_mfma_f32_16x16x32_bf16 v[46:49], v[158:161], v[200:203], v[46:49]
	v_mfma_f32_16x16x32_bf16 v[38:41], v[150:153], v[208:211], v[38:41]
	v_mfma_f32_16x16x32_bf16 v[28:31], v[158:161], v[208:211], v[28:31]
	v_mfma_f32_16x16x32_bf16 v[20:23], v[150:153], v[220:223], v[20:23]
	v_mfma_f32_16x16x32_bf16 v[12:15], v[158:161], v[220:223], v[12:15]
	v_mfma_f32_16x16x32_bf16 v[50:53], v[162:165], v[188:191], v[50:53]
	v_mfma_f32_16x16x32_bf16 v[42:45], v[180:183], v[188:191], v[42:45]
	v_mfma_f32_16x16x32_bf16 v[34:37], v[162:165], v[196:199], v[34:37]
	v_mfma_f32_16x16x32_bf16 v[24:27], v[180:183], v[196:199], v[24:27]
	v_mfma_f32_16x16x32_bf16 v[16:19], v[162:165], v[204:207], v[16:19]
	v_mfma_f32_16x16x32_bf16 v[8:11], v[180:183], v[204:207], v[8:11]
	v_mfma_f32_16x16x32_bf16 v[4:7], v[162:165], v[212:215], v[4:7]
	v_mfma_f32_16x16x32_bf16 v[0:3], v[180:183], v[212:215], v[0:3]
	v_mfma_f32_16x16x32_bf16 v[50:53], v[176:179], v[192:195], v[50:53]
	v_mfma_f32_16x16x32_bf16 v[42:45], v[184:187], v[192:195], v[42:45]
	v_mfma_f32_16x16x32_bf16 v[34:37], v[176:179], v[200:203], v[34:37]
	v_mfma_f32_16x16x32_bf16 v[24:27], v[184:187], v[200:203], v[24:27]
	v_mfma_f32_16x16x32_bf16 v[16:19], v[176:179], v[208:211], v[16:19]
	v_mfma_f32_16x16x32_bf16 v[8:11], v[184:187], v[208:211], v[8:11]
	v_mfma_f32_16x16x32_bf16 v[4:7], v[176:179], v[220:223], v[4:7]
	v_mfma_f32_16x16x32_bf16 v[0:3], v[184:187], v[220:223], v[0:3]
	s_barrier
	s_add_i32 s91, 0, 0x18000
	v_add_u32_e32 v145, s91, v143
	s_add_i32 vcc_lo, 0, 0x1c000
	ds_read_b128 v[146:149], v145
	ds_read_b128 v[150:153], v145 offset:1024
	ds_read_b128 v[154:157], v145 offset:2048
	ds_read_b128 v[158:161], v145 offset:3072
	v_add_u32_e32 v145, vcc_lo, v143
	ds_read_b128 v[162:165], v145
	ds_read_b128 v[176:179], v145 offset:1024
	ds_read_b128 v[180:183], v145 offset:2048
	ds_read_b128 v[184:187], v145 offset:3072
	s_add_u32 s54, s60, 0xb0000
	s_addc_u32 s55, s61, 0
	s_mov_b32 m0, s63
	ds_read_b128 v[188:191], v144 offset:32768
	ds_read_b128 v[192:195], v144 offset:33792
	ds_read_b128 v[196:199], v144 offset:34816
	ds_read_b128 v[200:203], v144 offset:35840
	ds_read_b128 v[204:207], v144 offset:36864
	ds_read_b128 v[208:211], v144 offset:37888
	ds_read_b128 v[212:215], v144 offset:38912
	ds_read_b128 v[220:223], v144 offset:39936
	global_load_lds_dwordx4 v130, s[54:55]
	s_mov_b32 m0, s64
	s_nop 0
	global_load_lds_dwordx4 v132, s[54:55]
	s_waitcnt vmcnt(8)
	s_waitcnt lgkmcnt(0)
	s_barrier
	v_mfma_f32_16x16x32_bf16 v[126:129], v[146:149], v[188:191], v[126:129]
	v_mfma_f32_16x16x32_bf16 v[122:125], v[154:157], v[188:191], v[122:125]
	v_mfma_f32_16x16x32_bf16 v[118:121], v[146:149], v[196:199], v[118:121]
	v_mfma_f32_16x16x32_bf16 v[110:113], v[154:157], v[196:199], v[110:113]
	v_mfma_f32_16x16x32_bf16 v[102:105], v[146:149], v[204:207], v[102:105]
	v_mfma_f32_16x16x32_bf16 v[94:97], v[154:157], v[204:207], v[94:97]
	v_mfma_f32_16x16x32_bf16 v[86:89], v[146:149], v[212:215], v[86:89]
	v_mfma_f32_16x16x32_bf16 v[78:81], v[154:157], v[212:215], v[78:81]
	v_mfma_f32_16x16x32_bf16 v[126:129], v[150:153], v[192:195], v[126:129]
	v_mfma_f32_16x16x32_bf16 v[122:125], v[158:161], v[192:195], v[122:125]
	v_mfma_f32_16x16x32_bf16 v[118:121], v[150:153], v[200:203], v[118:121]
	v_mfma_f32_16x16x32_bf16 v[110:113], v[158:161], v[200:203], v[110:113]
	v_mfma_f32_16x16x32_bf16 v[102:105], v[150:153], v[208:211], v[102:105]
	v_mfma_f32_16x16x32_bf16 v[94:97], v[158:161], v[208:211], v[94:97]
	v_mfma_f32_16x16x32_bf16 v[86:89], v[150:153], v[220:223], v[86:89]
	v_mfma_f32_16x16x32_bf16 v[78:81], v[158:161], v[220:223], v[78:81]
	v_mfma_f32_16x16x32_bf16 v[114:117], v[162:165], v[188:191], v[114:117]
	v_mfma_f32_16x16x32_bf16 v[106:109], v[180:183], v[188:191], v[106:109]
	v_mfma_f32_16x16x32_bf16 v[98:101], v[162:165], v[196:199], v[98:101]
	v_mfma_f32_16x16x32_bf16 v[90:93], v[180:183], v[196:199], v[90:93]
	v_mfma_f32_16x16x32_bf16 v[82:85], v[162:165], v[204:207], v[82:85]
	v_mfma_f32_16x16x32_bf16 v[74:77], v[180:183], v[204:207], v[74:77]
	v_mfma_f32_16x16x32_bf16 v[70:73], v[162:165], v[212:215], v[70:73]
	v_mfma_f32_16x16x32_bf16 v[66:69], v[180:183], v[212:215], v[66:69]
	v_mfma_f32_16x16x32_bf16 v[114:117], v[176:179], v[192:195], v[114:117]
	v_mfma_f32_16x16x32_bf16 v[106:109], v[184:187], v[192:195], v[106:109]
	v_mfma_f32_16x16x32_bf16 v[98:101], v[176:179], v[200:203], v[98:101]
	v_mfma_f32_16x16x32_bf16 v[90:93], v[184:187], v[200:203], v[90:93]
	v_mfma_f32_16x16x32_bf16 v[82:85], v[176:179], v[208:211], v[82:85]
	v_mfma_f32_16x16x32_bf16 v[74:77], v[184:187], v[208:211], v[74:77]
	v_mfma_f32_16x16x32_bf16 v[70:73], v[176:179], v[220:223], v[70:73]
	v_mfma_f32_16x16x32_bf16 v[66:69], v[184:187], v[220:223], v[66:69]
	s_barrier
	s_add_i32 s54, s91, s38
	s_mov_b32 m0, s54
	ds_read_b128 v[188:191], v144 offset:49152
	ds_read_b128 v[192:195], v144 offset:50176
	ds_read_b128 v[196:199], v144 offset:51200
	ds_read_b128 v[200:203], v144 offset:52224
	ds_read_b128 v[204:207], v144 offset:53248
	ds_read_b128 v[208:211], v144 offset:54272
	ds_read_b128 v[212:215], v144 offset:55296
	ds_read_b128 v[220:223], v144 offset:56320
	global_load_lds_dwordx4 v32, s[98:99]
	s_add_i32 m0, s54, 0x2000
	s_add_u32 s54, s58, 0xb0080
	s_addc_u32 s55, s59, 0
	s_add_i32 s58, vcc_lo, s38
	global_load_lds_dwordx4 v134, s[98:99]
	s_mov_b32 m0, s58
	s_nop 0
	global_load_lds_dwordx4 v32, s[54:55]
	s_add_i32 m0, s58, 0x2000
	s_nop 0
	global_load_lds_dwordx4 v134, s[54:55]
	s_mov_b32 m0, s67
	s_nop 0
	global_load_lds_dwordx4 v130, s[100:101]
	s_mov_b32 m0, s77
	s_nop 0
	global_load_lds_dwordx4 v132, s[100:101]
	s_waitcnt vmcnt(8)
	s_waitcnt lgkmcnt(0)
	s_barrier
	v_mfma_f32_16x16x32_bf16 v[62:65], v[146:149], v[188:191], v[62:65]
	v_mfma_f32_16x16x32_bf16 v[58:61], v[154:157], v[188:191], v[58:61]
	v_mfma_f32_16x16x32_bf16 v[54:57], v[146:149], v[196:199], v[54:57]
	v_mfma_f32_16x16x32_bf16 v[46:49], v[154:157], v[196:199], v[46:49]
	v_mfma_f32_16x16x32_bf16 v[38:41], v[146:149], v[204:207], v[38:41]
	v_mfma_f32_16x16x32_bf16 v[28:31], v[154:157], v[204:207], v[28:31]
	v_mfma_f32_16x16x32_bf16 v[20:23], v[146:149], v[212:215], v[20:23]
	v_mfma_f32_16x16x32_bf16 v[12:15], v[154:157], v[212:215], v[12:15]
	v_mfma_f32_16x16x32_bf16 v[62:65], v[150:153], v[192:195], v[62:65]
	v_mfma_f32_16x16x32_bf16 v[58:61], v[158:161], v[192:195], v[58:61]
	v_mfma_f32_16x16x32_bf16 v[54:57], v[150:153], v[200:203], v[54:57]
	v_mfma_f32_16x16x32_bf16 v[46:49], v[158:161], v[200:203], v[46:49]
	v_mfma_f32_16x16x32_bf16 v[38:41], v[150:153], v[208:211], v[38:41]
	v_mfma_f32_16x16x32_bf16 v[28:31], v[158:161], v[208:211], v[28:31]
	v_mfma_f32_16x16x32_bf16 v[20:23], v[150:153], v[220:223], v[20:23]
	v_mfma_f32_16x16x32_bf16 v[12:15], v[158:161], v[220:223], v[12:15]
	v_mfma_f32_16x16x32_bf16 v[50:53], v[162:165], v[188:191], v[50:53]
	v_mfma_f32_16x16x32_bf16 v[42:45], v[180:183], v[188:191], v[42:45]
	v_mfma_f32_16x16x32_bf16 v[34:37], v[162:165], v[196:199], v[34:37]
	v_mfma_f32_16x16x32_bf16 v[24:27], v[180:183], v[196:199], v[24:27]
	v_mfma_f32_16x16x32_bf16 v[16:19], v[162:165], v[204:207], v[16:19]
	v_mfma_f32_16x16x32_bf16 v[8:11], v[180:183], v[204:207], v[8:11]
	v_mfma_f32_16x16x32_bf16 v[4:7], v[162:165], v[212:215], v[4:7]
	v_mfma_f32_16x16x32_bf16 v[0:3], v[180:183], v[212:215], v[0:3]
	v_mfma_f32_16x16x32_bf16 v[50:53], v[176:179], v[192:195], v[50:53]
	v_mfma_f32_16x16x32_bf16 v[42:45], v[184:187], v[192:195], v[42:45]
	v_mfma_f32_16x16x32_bf16 v[34:37], v[176:179], v[200:203], v[34:37]
	v_mfma_f32_16x16x32_bf16 v[24:27], v[184:187], v[200:203], v[24:27]
	v_mfma_f32_16x16x32_bf16 v[16:19], v[176:179], v[208:211], v[16:19]
	v_mfma_f32_16x16x32_bf16 v[8:11], v[184:187], v[208:211], v[8:11]
	v_mfma_f32_16x16x32_bf16 v[4:7], v[176:179], v[220:223], v[4:7]
	v_mfma_f32_16x16x32_bf16 v[0:3], v[184:187], v[220:223], v[0:3]
	s_barrier
	s_add_u32 s47, s47, 0x100
	s_addc_u32 s89, s89, 0
	s_cmp_ge_i32 s90, s84
	s_mov_b64 s[54:55], s[56:57]
	s_mov_b32 s58, s90
	s_cbranch_scc0 .LBB0_184
	s_and_b64 vcc, exec, s[26:27]
	s_cbranch_vccz .LBB0_187
	s_barrier

.LBB0_202:
	s_add_u32 s51, s62, 0xfffc0080
	s_addc_u32 s66, s63, -1
	s_add_i32 s79, 0, 0x10000
	s_cmp_eq_u32 s27, 12
	s_cselect_b32 vcc_hi, s59, s66
	s_cselect_b32 vcc_lo, s58, s51
	v_add_u32_e32 v140, s79, v143
	s_cselect_b32 s67, s61, s19
	s_cselect_b32 s66, s60, s18
	s_add_i32 s51, 0, 0x14000
	ds_read_b128 v[146:149], v140
	ds_read_b128 v[150:153], v140 offset:1024
	ds_read_b128 v[154:157], v140 offset:2048
	ds_read_b128 v[158:161], v140 offset:3072
	v_add_u32_e32 v140, s51, v143
	ds_read_b128 v[162:165], v140
	ds_read_b128 v[176:179], v140 offset:1024
	ds_read_b128 v[180:183], v140 offset:2048
	ds_read_b128 v[184:187], v140 offset:3072
	s_add_i32 m0, s33, 0xc000
	ds_read_b128 v[188:191], v144
	ds_read_b128 v[192:195], v144 offset:1024
	ds_read_b128 v[196:199], v144 offset:2048
	ds_read_b128 v[200:203], v144 offset:3072
	ds_read_b128 v[204:207], v144 offset:4096
	ds_read_b128 v[208:211], v144 offset:5120
	ds_read_b128 v[212:215], v144 offset:6144
	ds_read_b128 v[220:223], v144 offset:7168
	global_load_lds_dwordx4 v136, s[62:63]
	s_add_i32 m0, s33, 0xe000
	s_nop 0
	global_load_lds_dwordx4 v138, s[62:63]
	s_waitcnt vmcnt(8)
	s_waitcnt lgkmcnt(0)
	s_barrier
	v_mfma_f32_16x16x32_bf16 v[126:129], v[146:149], v[188:191], v[126:129]
	v_mfma_f32_16x16x32_bf16 v[118:121], v[154:157], v[188:191], v[118:121]
	v_mfma_f32_16x16x32_bf16 v[110:113], v[146:149], v[196:199], v[110:113]
	v_mfma_f32_16x16x32_bf16 v[102:105], v[154:157], v[196:199], v[102:105]
	v_mfma_f32_16x16x32_bf16 v[94:97], v[146:149], v[204:207], v[94:97]
	v_mfma_f32_16x16x32_bf16 v[86:89], v[154:157], v[204:207], v[86:89]
	v_mfma_f32_16x16x32_bf16 v[78:81], v[146:149], v[212:215], v[78:81]
	v_mfma_f32_16x16x32_bf16 v[70:73], v[154:157], v[212:215], v[70:73]
	v_mfma_f32_16x16x32_bf16 v[126:129], v[150:153], v[192:195], v[126:129]
	v_mfma_f32_16x16x32_bf16 v[118:121], v[158:161], v[192:195], v[118:121]
	v_mfma_f32_16x16x32_bf16 v[110:113], v[150:153], v[200:203], v[110:113]
	v_mfma_f32_16x16x32_bf16 v[102:105], v[158:161], v[200:203], v[102:105]
	v_mfma_f32_16x16x32_bf16 v[94:97], v[150:153], v[208:211], v[94:97]
	v_mfma_f32_16x16x32_bf16 v[86:89], v[158:161], v[208:211], v[86:89]
	v_mfma_f32_16x16x32_bf16 v[78:81], v[150:153], v[220:223], v[78:81]
	v_mfma_f32_16x16x32_bf16 v[70:73], v[158:161], v[220:223], v[70:73]
	v_mfma_f32_16x16x32_bf16 v[122:125], v[162:165], v[188:191], v[122:125]
	v_mfma_f32_16x16x32_bf16 v[114:117], v[180:183], v[188:191], v[114:117]
	v_mfma_f32_16x16x32_bf16 v[106:109], v[162:165], v[196:199], v[106:109]
	v_mfma_f32_16x16x32_bf16 v[98:101], v[180:183], v[196:199], v[98:101]
	v_mfma_f32_16x16x32_bf16 v[90:93], v[162:165], v[204:207], v[90:93]
	v_mfma_f32_16x16x32_bf16 v[82:85], v[180:183], v[204:207], v[82:85]
	v_mfma_f32_16x16x32_bf16 v[74:77], v[162:165], v[212:215], v[74:77]
	v_mfma_f32_16x16x32_bf16 v[66:69], v[180:183], v[212:215], v[66:69]
	v_mfma_f32_16x16x32_bf16 v[122:125], v[176:179], v[192:195], v[122:125]
	v_mfma_f32_16x16x32_bf16 v[114:117], v[184:187], v[192:195], v[114:117]
	v_mfma_f32_16x16x32_bf16 v[106:109], v[176:179], v[200:203], v[106:109]
	v_mfma_f32_16x16x32_bf16 v[98:101], v[184:187], v[200:203], v[98:101]
	v_mfma_f32_16x16x32_bf16 v[90:93], v[176:179], v[208:211], v[90:93]
	v_mfma_f32_16x16x32_bf16 v[82:85], v[184:187], v[208:211], v[82:85]
	v_mfma_f32_16x16x32_bf16 v[74:77], v[176:179], v[220:223], v[74:77]
	v_mfma_f32_16x16x32_bf16 v[66:69], v[184:187], v[220:223], v[66:69]
	s_barrier
	s_add_u32 s98, s66, s28
	s_addc_u32 s99, s67, s29
	s_add_u32 s100, vcc_lo, s28
	s_addc_u32 s101, vcc_hi, s29
	s_add_i32 s79, s79, s1
	s_mov_b32 m0, s79
	ds_read_b128 v[188:191], v144 offset:16384
	ds_read_b128 v[192:195], v144 offset:17408
	ds_read_b128 v[196:199], v144 offset:18432
	ds_read_b128 v[200:203], v144 offset:19456
	ds_read_b128 v[204:207], v144 offset:20480
	ds_read_b128 v[208:211], v144 offset:21504
	ds_read_b128 v[212:215], v144 offset:22528
	ds_read_b128 v[220:223], v144 offset:23552
	global_load_lds_dwordx4 v32, s[66:67]
	s_add_i32 m0, s79, 0x2000
	s_add_u32 s84, s66, 0x40000
	s_addc_u32 s85, s67, 0
	s_add_i32 s51, s51, s1
	global_load_lds_dwordx4 v130, s[66:67]
	s_mov_b32 m0, s51
	s_nop 0
	global_load_lds_dwordx4 v32, s[84:85]
	s_add_i32 m0, s51, 0x2000
	s_nop 0
	global_load_lds_dwordx4 v130, s[84:85]
	s_mov_b32 m0, s33
	s_nop 0
	global_load_lds_dwordx4 v134, vcc
	s_mov_b32 m0, s38
	s_nop 0
	global_load_lds_dwordx4 v132, vcc
	s_waitcnt vmcnt(8)
	s_waitcnt lgkmcnt(0)
	s_barrier
	v_mfma_f32_16x16x32_bf16 v[62:65], v[146:149], v[188:191], v[62:65]
	v_mfma_f32_16x16x32_bf16 v[54:57], v[154:157], v[188:191], v[54:57]
	v_mfma_f32_16x16x32_bf16 v[46:49], v[146:149], v[196:199], v[46:49]
	v_mfma_f32_16x16x32_bf16 v[38:41], v[154:157], v[196:199], v[38:41]
	v_mfma_f32_16x16x32_bf16 v[28:31], v[146:149], v[204:207], v[28:31]
	v_mfma_f32_16x16x32_bf16 v[20:23], v[154:157], v[204:207], v[20:23]
	v_mfma_f32_16x16x32_bf16 v[12:15], v[146:149], v[212:215], v[12:15]
	v_mfma_f32_16x16x32_bf16 v[4:7], v[154:157], v[212:215], v[4:7]
	v_mfma_f32_16x16x32_bf16 v[62:65], v[150:153], v[192:195], v[62:65]
	v_mfma_f32_16x16x32_bf16 v[54:57], v[158:161], v[192:195], v[54:57]
	v_mfma_f32_16x16x32_bf16 v[46:49], v[150:153], v[200:203], v[46:49]
	v_mfma_f32_16x16x32_bf16 v[38:41], v[158:161], v[200:203], v[38:41]
	v_mfma_f32_16x16x32_bf16 v[28:31], v[150:153], v[208:211], v[28:31]
	v_mfma_f32_16x16x32_bf16 v[20:23], v[158:161], v[208:211], v[20:23]
	v_mfma_f32_16x16x32_bf16 v[12:15], v[150:153], v[220:223], v[12:15]
	v_mfma_f32_16x16x32_bf16 v[4:7], v[158:161], v[220:223], v[4:7]
	v_mfma_f32_16x16x32_bf16 v[58:61], v[162:165], v[188:191], v[58:61]
	v_mfma_f32_16x16x32_bf16 v[50:53], v[180:183], v[188:191], v[50:53]
	v_mfma_f32_16x16x32_bf16 v[42:45], v[162:165], v[196:199], v[42:45]
	v_mfma_f32_16x16x32_bf16 v[34:37], v[180:183], v[196:199], v[34:37]
	v_mfma_f32_16x16x32_bf16 v[24:27], v[162:165], v[204:207], v[24:27]
	v_mfma_f32_16x16x32_bf16 v[16:19], v[180:183], v[204:207], v[16:19]
	v_mfma_f32_16x16x32_bf16 v[8:11], v[162:165], v[212:215], v[8:11]
	v_mfma_f32_16x16x32_bf16 v[0:3], v[180:183], v[212:215], v[0:3]
	v_mfma_f32_16x16x32_bf16 v[58:61], v[176:179], v[192:195], v[58:61]
	v_mfma_f32_16x16x32_bf16 v[50:53], v[184:187], v[192:195], v[50:53]
	v_mfma_f32_16x16x32_bf16 v[42:45], v[176:179], v[200:203], v[42:45]
	v_mfma_f32_16x16x32_bf16 v[34:37], v[184:187], v[200:203], v[34:37]
	v_mfma_f32_16x16x32_bf16 v[24:27], v[176:179], v[208:211], v[24:27]
	v_mfma_f32_16x16x32_bf16 v[16:19], v[184:187], v[208:211], v[16:19]
	v_mfma_f32_16x16x32_bf16 v[8:11], v[176:179], v[220:223], v[8:11]
	v_mfma_f32_16x16x32_bf16 v[0:3], v[184:187], v[220:223], v[0:3]
	s_barrier
	s_add_i32 s51, 0, 0x18000
	v_add_u32_e32 v145, s51, v143
	s_add_i32 s79, 0, 0x1c000
	ds_read_b128 v[146:149], v145
	ds_read_b128 v[150:153], v145 offset:1024
	ds_read_b128 v[154:157], v145 offset:2048
	ds_read_b128 v[158:161], v145 offset:3072
	v_add_u32_e32 v145, s79, v143
	ds_read_b128 v[162:165], v145
	ds_read_b128 v[176:179], v145 offset:1024
	ds_read_b128 v[180:183], v145 offset:2048
	ds_read_b128 v[184:187], v145 offset:3072
	s_add_u32 s84, vcc_lo, 0x40000
	s_addc_u32 s85, vcc_hi, 0
	s_mov_b32 m0, s39
	ds_read_b128 v[188:191], v144 offset:32768
	ds_read_b128 v[192:195], v144 offset:33792
	ds_read_b128 v[196:199], v144 offset:34816
	ds_read_b128 v[200:203], v144 offset:35840
	ds_read_b128 v[204:207], v144 offset:36864
	ds_read_b128 v[208:211], v144 offset:37888
	ds_read_b128 v[212:215], v144 offset:38912
	ds_read_b128 v[220:223], v144 offset:39936
	global_load_lds_dwordx4 v134, s[84:85]
	s_mov_b32 m0, s46
	s_nop 0
	global_load_lds_dwordx4 v132, s[84:85]
	s_waitcnt vmcnt(8)
	s_waitcnt lgkmcnt(0)
	s_barrier
	v_mfma_f32_16x16x32_bf16 v[126:129], v[146:149], v[188:191], v[126:129]
	v_mfma_f32_16x16x32_bf16 v[118:121], v[154:157], v[188:191], v[118:121]
	v_mfma_f32_16x16x32_bf16 v[110:113], v[146:149], v[196:199], v[110:113]
	v_mfma_f32_16x16x32_bf16 v[102:105], v[154:157], v[196:199], v[102:105]
	v_mfma_f32_16x16x32_bf16 v[94:97], v[146:149], v[204:207], v[94:97]
	v_mfma_f32_16x16x32_bf16 v[86:89], v[154:157], v[204:207], v[86:89]
	v_mfma_f32_16x16x32_bf16 v[78:81], v[146:149], v[212:215], v[78:81]
	v_mfma_f32_16x16x32_bf16 v[70:73], v[154:157], v[212:215], v[70:73]
	v_mfma_f32_16x16x32_bf16 v[126:129], v[150:153], v[192:195], v[126:129]
	v_mfma_f32_16x16x32_bf16 v[118:121], v[158:161], v[192:195], v[118:121]
	v_mfma_f32_16x16x32_bf16 v[110:113], v[150:153], v[200:203], v[110:113]
	v_mfma_f32_16x16x32_bf16 v[102:105], v[158:161], v[200:203], v[102:105]
	v_mfma_f32_16x16x32_bf16 v[94:97], v[150:153], v[208:211], v[94:97]
	v_mfma_f32_16x16x32_bf16 v[86:89], v[158:161], v[208:211], v[86:89]
	v_mfma_f32_16x16x32_bf16 v[78:81], v[150:153], v[220:223], v[78:81]
	v_mfma_f32_16x16x32_bf16 v[70:73], v[158:161], v[220:223], v[70:73]
	v_mfma_f32_16x16x32_bf16 v[122:125], v[162:165], v[188:191], v[122:125]
	v_mfma_f32_16x16x32_bf16 v[114:117], v[180:183], v[188:191], v[114:117]
	v_mfma_f32_16x16x32_bf16 v[106:109], v[162:165], v[196:199], v[106:109]
	v_mfma_f32_16x16x32_bf16 v[98:101], v[180:183], v[196:199], v[98:101]
	v_mfma_f32_16x16x32_bf16 v[90:93], v[162:165], v[204:207], v[90:93]
	v_mfma_f32_16x16x32_bf16 v[82:85], v[180:183], v[204:207], v[82:85]
	v_mfma_f32_16x16x32_bf16 v[74:77], v[162:165], v[212:215], v[74:77]
	v_mfma_f32_16x16x32_bf16 v[66:69], v[180:183], v[212:215], v[66:69]
	v_mfma_f32_16x16x32_bf16 v[122:125], v[176:179], v[192:195], v[122:125]
	v_mfma_f32_16x16x32_bf16 v[114:117], v[184:187], v[192:195], v[114:117]
	v_mfma_f32_16x16x32_bf16 v[106:109], v[176:179], v[200:203], v[106:109]
	v_mfma_f32_16x16x32_bf16 v[98:101], v[184:187], v[200:203], v[98:101]
	v_mfma_f32_16x16x32_bf16 v[90:93], v[176:179], v[208:211], v[90:93]
	v_mfma_f32_16x16x32_bf16 v[82:85], v[184:187], v[208:211], v[82:85]
	v_mfma_f32_16x16x32_bf16 v[74:77], v[176:179], v[220:223], v[74:77]
	v_mfma_f32_16x16x32_bf16 v[66:69], v[184:187], v[220:223], v[66:69]
	s_barrier
	s_add_i32 s51, s51, s1
	s_mov_b32 m0, s51
	ds_read_b128 v[188:191], v144 offset:49152
	ds_read_b128 v[192:195], v144 offset:50176
	ds_read_b128 v[196:199], v144 offset:51200
	ds_read_b128 v[200:203], v144 offset:52224
	ds_read_b128 v[204:207], v144 offset:53248
	ds_read_b128 v[208:211], v144 offset:54272
	ds_read_b128 v[212:215], v144 offset:55296
	ds_read_b128 v[220:223], v144 offset:56320
	global_load_lds_dwordx4 v32, s[98:99]
	s_add_i32 m0, s51, 0x2000
	s_add_u32 s66, s66, 0x40080
	s_addc_u32 s67, s67, 0
	s_add_i32 s51, s79, s1
	global_load_lds_dwordx4 v130, s[98:99]
	s_mov_b32 m0, s51
	s_nop 0
	global_load_lds_dwordx4 v32, s[66:67]
	s_add_i32 m0, s51, 0x2000
	s_nop 0
	global_load_lds_dwordx4 v130, s[66:67]
	s_mov_b32 m0, s64
	s_nop 0
	global_load_lds_dwordx4 v134, s[100:101]
	s_mov_b32 m0, s65
	s_nop 0
	global_load_lds_dwordx4 v132, s[100:101]
	s_waitcnt vmcnt(8)
	s_waitcnt lgkmcnt(0)
	s_barrier
	v_mfma_f32_16x16x32_bf16 v[62:65], v[146:149], v[188:191], v[62:65]
	v_mfma_f32_16x16x32_bf16 v[54:57], v[154:157], v[188:191], v[54:57]
	v_mfma_f32_16x16x32_bf16 v[46:49], v[146:149], v[196:199], v[46:49]
	v_mfma_f32_16x16x32_bf16 v[38:41], v[154:157], v[196:199], v[38:41]
	v_mfma_f32_16x16x32_bf16 v[28:31], v[146:149], v[204:207], v[28:31]
	v_mfma_f32_16x16x32_bf16 v[20:23], v[154:157], v[204:207], v[20:23]
	v_mfma_f32_16x16x32_bf16 v[12:15], v[146:149], v[212:215], v[12:15]
	v_mfma_f32_16x16x32_bf16 v[4:7], v[154:157], v[212:215], v[4:7]
	v_mfma_f32_16x16x32_bf16 v[62:65], v[150:153], v[192:195], v[62:65]
	v_mfma_f32_16x16x32_bf16 v[54:57], v[158:161], v[192:195], v[54:57]
	v_mfma_f32_16x16x32_bf16 v[46:49], v[150:153], v[200:203], v[46:49]
	v_mfma_f32_16x16x32_bf16 v[38:41], v[158:161], v[200:203], v[38:41]
	v_mfma_f32_16x16x32_bf16 v[28:31], v[150:153], v[208:211], v[28:31]
	v_mfma_f32_16x16x32_bf16 v[20:23], v[158:161], v[208:211], v[20:23]
	v_mfma_f32_16x16x32_bf16 v[12:15], v[150:153], v[220:223], v[12:15]
	v_mfma_f32_16x16x32_bf16 v[4:7], v[158:161], v[220:223], v[4:7]
	v_mfma_f32_16x16x32_bf16 v[58:61], v[162:165], v[188:191], v[58:61]
	v_mfma_f32_16x16x32_bf16 v[50:53], v[180:183], v[188:191], v[50:53]
	v_mfma_f32_16x16x32_bf16 v[42:45], v[162:165], v[196:199], v[42:45]
	v_mfma_f32_16x16x32_bf16 v[34:37], v[180:183], v[196:199], v[34:37]
	v_mfma_f32_16x16x32_bf16 v[24:27], v[162:165], v[204:207], v[24:27]
	v_mfma_f32_16x16x32_bf16 v[16:19], v[180:183], v[204:207], v[16:19]
	v_mfma_f32_16x16x32_bf16 v[8:11], v[162:165], v[212:215], v[8:11]
	v_mfma_f32_16x16x32_bf16 v[0:3], v[180:183], v[212:215], v[0:3]
	v_mfma_f32_16x16x32_bf16 v[58:61], v[176:179], v[192:195], v[58:61]
	v_mfma_f32_16x16x32_bf16 v[50:53], v[184:187], v[192:195], v[50:53]
	v_mfma_f32_16x16x32_bf16 v[42:45], v[176:179], v[200:203], v[42:45]
	v_mfma_f32_16x16x32_bf16 v[34:37], v[184:187], v[200:203], v[34:37]
	v_mfma_f32_16x16x32_bf16 v[24:27], v[176:179], v[208:211], v[24:27]
	v_mfma_f32_16x16x32_bf16 v[16:19], v[184:187], v[208:211], v[16:19]
	v_mfma_f32_16x16x32_bf16 v[8:11], v[176:179], v[220:223], v[8:11]
	v_mfma_f32_16x16x32_bf16 v[0:3], v[184:187], v[220:223], v[0:3]
	s_barrier
	s_add_i32 s27, s27, 2
	s_add_u32 s62, s62, 0x100
	s_addc_u32 s63, s63, 0
	s_add_u32 s18, s18, 0x100
	s_addc_u32 s19, s19, 0
	s_cmp_gt_u32 s27, 13
	s_cbranch_scc0 .LBB0_202
	s_and_b64 vcc, exec, s[24:25]
	s_cbranch_vccz .LBB0_205
	s_barrier

.LBB0_333:
	s_add_i32 s66, s52, 2
	s_add_u32 s53, s50, 0xfffc0080
	s_addc_u32 s54, s51, -1
	s_add_i32 s67, 0, 0x10000
	s_cmp_eq_u32 s27, s52
	s_cselect_b32 s55, s18, s54
	s_cselect_b32 s54, s19, s53
	v_add_u32_e32 v140, s67, v143
	s_cselect_b32 s53, s22, s65
	s_cselect_b32 s52, s23, s64
	s_add_i32 s69, 0, 0x14000
	ds_read_b128 v[146:149], v140
	ds_read_b128 v[150:153], v140 offset:1024
	ds_read_b128 v[154:157], v140 offset:2048
	ds_read_b128 v[158:161], v140 offset:3072
	v_add_u32_e32 v140, s69, v143
	ds_read_b128 v[162:165], v140
	ds_read_b128 v[176:179], v140 offset:1024
	ds_read_b128 v[180:183], v140 offset:2048
	ds_read_b128 v[184:187], v140 offset:3072
	s_add_i32 m0, s33, 0xc000
	ds_read_b128 v[188:191], v144
	ds_read_b128 v[192:195], v144 offset:1024
	ds_read_b128 v[196:199], v144 offset:2048
	ds_read_b128 v[200:203], v144 offset:3072
	ds_read_b128 v[204:207], v144 offset:4096
	ds_read_b128 v[208:211], v144 offset:5120
	ds_read_b128 v[212:215], v144 offset:6144
	ds_read_b128 v[220:223], v144 offset:7168
	global_load_lds_dwordx4 v136, s[50:51]
	s_add_i32 m0, s33, 0xe000
	s_nop 0
	global_load_lds_dwordx4 v138, s[50:51]
	s_waitcnt vmcnt(8)
	s_waitcnt lgkmcnt(0)
	s_barrier
	v_mfma_f32_16x16x32_bf16 v[126:129], v[146:149], v[188:191], v[126:129]
	v_mfma_f32_16x16x32_bf16 v[122:125], v[154:157], v[188:191], v[122:125]
	v_mfma_f32_16x16x32_bf16 v[118:121], v[146:149], v[196:199], v[118:121]
	v_mfma_f32_16x16x32_bf16 v[110:113], v[154:157], v[196:199], v[110:113]
	v_mfma_f32_16x16x32_bf16 v[102:105], v[146:149], v[204:207], v[102:105]
	v_mfma_f32_16x16x32_bf16 v[94:97], v[154:157], v[204:207], v[94:97]
	v_mfma_f32_16x16x32_bf16 v[86:89], v[146:149], v[212:215], v[86:89]
	v_mfma_f32_16x16x32_bf16 v[78:81], v[154:157], v[212:215], v[78:81]
	v_mfma_f32_16x16x32_bf16 v[126:129], v[150:153], v[192:195], v[126:129]
	v_mfma_f32_16x16x32_bf16 v[122:125], v[158:161], v[192:195], v[122:125]
	v_mfma_f32_16x16x32_bf16 v[118:121], v[150:153], v[200:203], v[118:121]
	v_mfma_f32_16x16x32_bf16 v[110:113], v[158:161], v[200:203], v[110:113]
	v_mfma_f32_16x16x32_bf16 v[102:105], v[150:153], v[208:211], v[102:105]
	v_mfma_f32_16x16x32_bf16 v[94:97], v[158:161], v[208:211], v[94:97]
	v_mfma_f32_16x16x32_bf16 v[86:89], v[150:153], v[220:223], v[86:89]
	v_mfma_f32_16x16x32_bf16 v[78:81], v[158:161], v[220:223], v[78:81]
	v_mfma_f32_16x16x32_bf16 v[114:117], v[162:165], v[188:191], v[114:117]
	v_mfma_f32_16x16x32_bf16 v[106:109], v[180:183], v[188:191], v[106:109]
	v_mfma_f32_16x16x32_bf16 v[98:101], v[162:165], v[196:199], v[98:101]
	v_mfma_f32_16x16x32_bf16 v[90:93], v[180:183], v[196:199], v[90:93]
	v_mfma_f32_16x16x32_bf16 v[82:85], v[162:165], v[204:207], v[82:85]
	v_mfma_f32_16x16x32_bf16 v[74:77], v[180:183], v[204:207], v[74:77]
	v_mfma_f32_16x16x32_bf16 v[70:73], v[162:165], v[212:215], v[70:73]
	v_mfma_f32_16x16x32_bf16 v[66:69], v[180:183], v[212:215], v[66:69]
	v_mfma_f32_16x16x32_bf16 v[114:117], v[176:179], v[192:195], v[114:117]
	v_mfma_f32_16x16x32_bf16 v[106:109], v[184:187], v[192:195], v[106:109]
	v_mfma_f32_16x16x32_bf16 v[98:101], v[176:179], v[200:203], v[98:101]
	v_mfma_f32_16x16x32_bf16 v[90:93], v[184:187], v[200:203], v[90:93]
	v_mfma_f32_16x16x32_bf16 v[82:85], v[176:179], v[208:211], v[82:85]
	v_mfma_f32_16x16x32_bf16 v[74:77], v[184:187], v[208:211], v[74:77]
	v_mfma_f32_16x16x32_bf16 v[70:73], v[176:179], v[220:223], v[70:73]
	v_mfma_f32_16x16x32_bf16 v[66:69], v[184:187], v[220:223], v[66:69]
	s_barrier
	s_add_u32 s98, s52, s28
	s_addc_u32 s99, s53, s29
	s_add_u32 s100, s54, s28
	s_addc_u32 s101, s55, s29
	s_add_i32 s67, s67, s13
	s_mov_b32 m0, s67
	ds_read_b128 v[188:191], v144 offset:16384
	ds_read_b128 v[192:195], v144 offset:17408
	ds_read_b128 v[196:199], v144 offset:18432
	ds_read_b128 v[200:203], v144 offset:19456
	ds_read_b128 v[204:207], v144 offset:20480
	ds_read_b128 v[208:211], v144 offset:21504
	ds_read_b128 v[212:215], v144 offset:22528
	ds_read_b128 v[220:223], v144 offset:23552
	global_load_lds_dwordx4 v32, s[52:53]
	s_add_i32 m0, s67, 0x2000
	s_add_u32 s78, s52, 0x40000
	s_addc_u32 s79, s53, 0
	s_add_i32 s67, s69, s13
	global_load_lds_dwordx4 v134, s[52:53]
	s_mov_b32 m0, s67
	s_nop 0
	global_load_lds_dwordx4 v32, s[78:79]
	s_add_i32 m0, s67, 0x2000
	s_nop 0
	global_load_lds_dwordx4 v134, s[78:79]
	s_mov_b32 m0, s33
	s_nop 0
	global_load_lds_dwordx4 v130, s[54:55]
	s_mov_b32 m0, s38
	s_nop 0
	global_load_lds_dwordx4 v132, s[54:55]
	s_waitcnt vmcnt(8)
	s_waitcnt lgkmcnt(0)
	s_barrier
	v_mfma_f32_16x16x32_bf16 v[62:65], v[146:149], v[188:191], v[62:65]
	v_mfma_f32_16x16x32_bf16 v[58:61], v[154:157], v[188:191], v[58:61]
	v_mfma_f32_16x16x32_bf16 v[54:57], v[146:149], v[196:199], v[54:57]
	v_mfma_f32_16x16x32_bf16 v[46:49], v[154:157], v[196:199], v[46:49]
	v_mfma_f32_16x16x32_bf16 v[38:41], v[146:149], v[204:207], v[38:41]
	v_mfma_f32_16x16x32_bf16 v[28:31], v[154:157], v[204:207], v[28:31]
	v_mfma_f32_16x16x32_bf16 v[20:23], v[146:149], v[212:215], v[20:23]
	v_mfma_f32_16x16x32_bf16 v[12:15], v[154:157], v[212:215], v[12:15]
	v_mfma_f32_16x16x32_bf16 v[62:65], v[150:153], v[192:195], v[62:65]
	v_mfma_f32_16x16x32_bf16 v[58:61], v[158:161], v[192:195], v[58:61]
	v_mfma_f32_16x16x32_bf16 v[54:57], v[150:153], v[200:203], v[54:57]
	v_mfma_f32_16x16x32_bf16 v[46:49], v[158:161], v[200:203], v[46:49]
	v_mfma_f32_16x16x32_bf16 v[38:41], v[150:153], v[208:211], v[38:41]
	v_mfma_f32_16x16x32_bf16 v[28:31], v[158:161], v[208:211], v[28:31]
	v_mfma_f32_16x16x32_bf16 v[20:23], v[150:153], v[220:223], v[20:23]
	v_mfma_f32_16x16x32_bf16 v[12:15], v[158:161], v[220:223], v[12:15]
	v_mfma_f32_16x16x32_bf16 v[50:53], v[162:165], v[188:191], v[50:53]
	v_mfma_f32_16x16x32_bf16 v[42:45], v[180:183], v[188:191], v[42:45]
	v_mfma_f32_16x16x32_bf16 v[34:37], v[162:165], v[196:199], v[34:37]
	v_mfma_f32_16x16x32_bf16 v[24:27], v[180:183], v[196:199], v[24:27]
	v_mfma_f32_16x16x32_bf16 v[16:19], v[162:165], v[204:207], v[16:19]
	v_mfma_f32_16x16x32_bf16 v[8:11], v[180:183], v[204:207], v[8:11]
	v_mfma_f32_16x16x32_bf16 v[4:7], v[162:165], v[212:215], v[4:7]
	v_mfma_f32_16x16x32_bf16 v[0:3], v[180:183], v[212:215], v[0:3]
	v_mfma_f32_16x16x32_bf16 v[50:53], v[176:179], v[192:195], v[50:53]
	v_mfma_f32_16x16x32_bf16 v[42:45], v[184:187], v[192:195], v[42:45]
	v_mfma_f32_16x16x32_bf16 v[34:37], v[176:179], v[200:203], v[34:37]
	v_mfma_f32_16x16x32_bf16 v[24:27], v[184:187], v[200:203], v[24:27]
	v_mfma_f32_16x16x32_bf16 v[16:19], v[176:179], v[208:211], v[16:19]
	v_mfma_f32_16x16x32_bf16 v[8:11], v[184:187], v[208:211], v[8:11]
	v_mfma_f32_16x16x32_bf16 v[4:7], v[176:179], v[220:223], v[4:7]
	v_mfma_f32_16x16x32_bf16 v[0:3], v[184:187], v[220:223], v[0:3]
	s_barrier
	s_add_i32 s67, 0, 0x18000
	v_add_u32_e32 v145, s67, v143
	s_add_i32 s69, 0, 0x1c000
	ds_read_b128 v[146:149], v145
	ds_read_b128 v[150:153], v145 offset:1024
	ds_read_b128 v[154:157], v145 offset:2048
	ds_read_b128 v[158:161], v145 offset:3072
	v_add_u32_e32 v145, s69, v143
	ds_read_b128 v[162:165], v145
	ds_read_b128 v[176:179], v145 offset:1024
	ds_read_b128 v[180:183], v145 offset:2048
	ds_read_b128 v[184:187], v145 offset:3072
	s_add_u32 s54, s54, 0x40000
	s_addc_u32 s55, s55, 0
	s_mov_b32 m0, s39
	ds_read_b128 v[188:191], v144 offset:32768
	ds_read_b128 v[192:195], v144 offset:33792
	ds_read_b128 v[196:199], v144 offset:34816
	ds_read_b128 v[200:203], v144 offset:35840
	ds_read_b128 v[204:207], v144 offset:36864
	ds_read_b128 v[208:211], v144 offset:37888
	ds_read_b128 v[212:215], v144 offset:38912
	ds_read_b128 v[220:223], v144 offset:39936
	global_load_lds_dwordx4 v130, s[54:55]
	s_mov_b32 m0, s46
	s_nop 0
	global_load_lds_dwordx4 v132, s[54:55]
	s_waitcnt vmcnt(8)
	s_waitcnt lgkmcnt(0)
	s_barrier
	v_mfma_f32_16x16x32_bf16 v[126:129], v[146:149], v[188:191], v[126:129]
	v_mfma_f32_16x16x32_bf16 v[122:125], v[154:157], v[188:191], v[122:125]
	v_mfma_f32_16x16x32_bf16 v[118:121], v[146:149], v[196:199], v[118:121]
	v_mfma_f32_16x16x32_bf16 v[110:113], v[154:157], v[196:199], v[110:113]
	v_mfma_f32_16x16x32_bf16 v[102:105], v[146:149], v[204:207], v[102:105]
	v_mfma_f32_16x16x32_bf16 v[94:97], v[154:157], v[204:207], v[94:97]
	v_mfma_f32_16x16x32_bf16 v[86:89], v[146:149], v[212:215], v[86:89]
	v_mfma_f32_16x16x32_bf16 v[78:81], v[154:157], v[212:215], v[78:81]
	v_mfma_f32_16x16x32_bf16 v[126:129], v[150:153], v[192:195], v[126:129]
	v_mfma_f32_16x16x32_bf16 v[122:125], v[158:161], v[192:195], v[122:125]
	v_mfma_f32_16x16x32_bf16 v[118:121], v[150:153], v[200:203], v[118:121]
	v_mfma_f32_16x16x32_bf16 v[110:113], v[158:161], v[200:203], v[110:113]
	v_mfma_f32_16x16x32_bf16 v[102:105], v[150:153], v[208:211], v[102:105]
	v_mfma_f32_16x16x32_bf16 v[94:97], v[158:161], v[208:211], v[94:97]
	v_mfma_f32_16x16x32_bf16 v[86:89], v[150:153], v[220:223], v[86:89]
	v_mfma_f32_16x16x32_bf16 v[78:81], v[158:161], v[220:223], v[78:81]
	v_mfma_f32_16x16x32_bf16 v[114:117], v[162:165], v[188:191], v[114:117]
	v_mfma_f32_16x16x32_bf16 v[106:109], v[180:183], v[188:191], v[106:109]
	v_mfma_f32_16x16x32_bf16 v[98:101], v[162:165], v[196:199], v[98:101]
	v_mfma_f32_16x16x32_bf16 v[90:93], v[180:183], v[196:199], v[90:93]
	v_mfma_f32_16x16x32_bf16 v[82:85], v[162:165], v[204:207], v[82:85]
	v_mfma_f32_16x16x32_bf16 v[74:77], v[180:183], v[204:207], v[74:77]
	v_mfma_f32_16x16x32_bf16 v[70:73], v[162:165], v[212:215], v[70:73]
	v_mfma_f32_16x16x32_bf16 v[66:69], v[180:183], v[212:215], v[66:69]
	v_mfma_f32_16x16x32_bf16 v[114:117], v[176:179], v[192:195], v[114:117]
	v_mfma_f32_16x16x32_bf16 v[106:109], v[184:187], v[192:195], v[106:109]
	v_mfma_f32_16x16x32_bf16 v[98:101], v[176:179], v[200:203], v[98:101]
	v_mfma_f32_16x16x32_bf16 v[90:93], v[184:187], v[200:203], v[90:93]
	v_mfma_f32_16x16x32_bf16 v[82:85], v[176:179], v[208:211], v[82:85]
	v_mfma_f32_16x16x32_bf16 v[74:77], v[184:187], v[208:211], v[74:77]
	v_mfma_f32_16x16x32_bf16 v[70:73], v[176:179], v[220:223], v[70:73]
	v_mfma_f32_16x16x32_bf16 v[66:69], v[184:187], v[220:223], v[66:69]
	s_barrier
	s_add_i32 s54, s67, s13
	s_mov_b32 m0, s54
	ds_read_b128 v[188:191], v144 offset:49152
	ds_read_b128 v[192:195], v144 offset:50176
	ds_read_b128 v[196:199], v144 offset:51200
	ds_read_b128 v[200:203], v144 offset:52224
	ds_read_b128 v[204:207], v144 offset:53248
	ds_read_b128 v[208:211], v144 offset:54272
	ds_read_b128 v[212:215], v144 offset:55296
	ds_read_b128 v[220:223], v144 offset:56320
	global_load_lds_dwordx4 v32, s[98:99]
	s_add_i32 m0, s54, 0x2000
	s_add_u32 s52, s52, 0x40080
	s_addc_u32 s53, s53, 0
	s_add_i32 s54, s69, s13
	global_load_lds_dwordx4 v134, s[98:99]
	s_mov_b32 m0, s54
	s_nop 0
	global_load_lds_dwordx4 v32, s[52:53]
	s_add_i32 m0, s54, 0x2000
	s_nop 0
	global_load_lds_dwordx4 v134, s[52:53]
	s_mov_b32 m0, s57
	s_nop 0
	global_load_lds_dwordx4 v130, s[100:101]
	s_mov_b32 m0, s58
	s_nop 0
	global_load_lds_dwordx4 v132, s[100:101]
	s_waitcnt vmcnt(8)
	s_waitcnt lgkmcnt(0)
	s_barrier
	v_mfma_f32_16x16x32_bf16 v[62:65], v[146:149], v[188:191], v[62:65]
	v_mfma_f32_16x16x32_bf16 v[58:61], v[154:157], v[188:191], v[58:61]
	v_mfma_f32_16x16x32_bf16 v[54:57], v[146:149], v[196:199], v[54:57]
	v_mfma_f32_16x16x32_bf16 v[46:49], v[154:157], v[196:199], v[46:49]
	v_mfma_f32_16x16x32_bf16 v[38:41], v[146:149], v[204:207], v[38:41]
	v_mfma_f32_16x16x32_bf16 v[28:31], v[154:157], v[204:207], v[28:31]
	v_mfma_f32_16x16x32_bf16 v[20:23], v[146:149], v[212:215], v[20:23]
	v_mfma_f32_16x16x32_bf16 v[12:15], v[154:157], v[212:215], v[12:15]
	v_mfma_f32_16x16x32_bf16 v[62:65], v[150:153], v[192:195], v[62:65]
	v_mfma_f32_16x16x32_bf16 v[58:61], v[158:161], v[192:195], v[58:61]
	v_mfma_f32_16x16x32_bf16 v[54:57], v[150:153], v[200:203], v[54:57]
	v_mfma_f32_16x16x32_bf16 v[46:49], v[158:161], v[200:203], v[46:49]
	v_mfma_f32_16x16x32_bf16 v[38:41], v[150:153], v[208:211], v[38:41]
	v_mfma_f32_16x16x32_bf16 v[28:31], v[158:161], v[208:211], v[28:31]
	v_mfma_f32_16x16x32_bf16 v[20:23], v[150:153], v[220:223], v[20:23]
	v_mfma_f32_16x16x32_bf16 v[12:15], v[158:161], v[220:223], v[12:15]
	v_mfma_f32_16x16x32_bf16 v[50:53], v[162:165], v[188:191], v[50:53]
	v_mfma_f32_16x16x32_bf16 v[42:45], v[180:183], v[188:191], v[42:45]
	v_mfma_f32_16x16x32_bf16 v[34:37], v[162:165], v[196:199], v[34:37]
	v_mfma_f32_16x16x32_bf16 v[24:27], v[180:183], v[196:199], v[24:27]
	v_mfma_f32_16x16x32_bf16 v[16:19], v[162:165], v[204:207], v[16:19]
	v_mfma_f32_16x16x32_bf16 v[8:11], v[180:183], v[204:207], v[8:11]
	v_mfma_f32_16x16x32_bf16 v[4:7], v[162:165], v[212:215], v[4:7]
	v_mfma_f32_16x16x32_bf16 v[0:3], v[180:183], v[212:215], v[0:3]
	v_mfma_f32_16x16x32_bf16 v[50:53], v[176:179], v[192:195], v[50:53]
	v_mfma_f32_16x16x32_bf16 v[42:45], v[184:187], v[192:195], v[42:45]
	v_mfma_f32_16x16x32_bf16 v[34:37], v[176:179], v[200:203], v[34:37]
	v_mfma_f32_16x16x32_bf16 v[24:27], v[184:187], v[200:203], v[24:27]
	v_mfma_f32_16x16x32_bf16 v[16:19], v[176:179], v[208:211], v[16:19]
	v_mfma_f32_16x16x32_bf16 v[8:11], v[184:187], v[208:211], v[8:11]
	v_mfma_f32_16x16x32_bf16 v[4:7], v[176:179], v[220:223], v[4:7]
	v_mfma_f32_16x16x32_bf16 v[0:3], v[184:187], v[220:223], v[0:3]
	s_barrier
	s_add_u32 s50, s50, 0x100
	s_addc_u32 s51, s51, 0
	s_add_u32 s64, s64, 0x100
	s_addc_u32 s65, s65, 0
	s_cmp_ge_i32 s66, s61
	s_mov_b32 s52, s66
	s_cbranch_scc0 .LBB0_333
	s_and_b64 vcc, exec, s[20:21]
	s_cbranch_vccz .LBB0_336
	s_barrier

.LBB0_381:
	s_add_i32 s42, s24, 2
	s_add_u32 s0, s20, 0xfffc0080
	s_addc_u32 s25, s21, -1
	s_add_i32 s90, 0, 0x10000
	s_cmp_eq_u32 s1, s24
	s_cselect_b32 s27, s61, s25
	s_cselect_b32 s26, s60, s0
	s_cselect_b32 s25, s63, s23
	s_cselect_b32 s24, s62, s22
	s_add_i32 s33, 0, 0x14000
	v_add_u32_e32 v172, s90, v169
	v_add_u32_e32 v174, s33, v169
	ds_read_b128 v[130:133], v172
	ds_read_b128 v[134:137], v172 offset:1024
	ds_read_b128 v[152:155], v172 offset:2048
	ds_read_b128 v[156:159], v172 offset:3072
	ds_read_b128 v[160:163], v174
	ds_read_b128 v[176:179], v174 offset:1024
	ds_read_b128 v[180:183], v174 offset:2048
	ds_read_b128 v[184:187], v174 offset:3072
	s_add_i32 s59, s77, 0xc000
	s_mov_b32 m0, s59
	s_add_i32 s89, s77, 0xe000
	ds_read_b128 v[188:191], v170
	ds_read_b128 v[192:195], v170 offset:1024
	ds_read_b128 v[196:199], v170 offset:2048
	ds_read_b128 v[200:203], v170 offset:3072
	ds_read_b128 v[204:207], v170 offset:4096
	ds_read_b128 v[208:211], v170 offset:5120
	ds_read_b128 v[212:215], v170 offset:6144
	ds_read_b128 v[220:223], v170 offset:7168
	global_load_lds_dwordx4 v144, s[20:21]
	s_mov_b32 m0, s89
	s_nop 0
	global_load_lds_dwordx4 v146, s[20:21]
	s_waitcnt vmcnt(8)
	s_waitcnt lgkmcnt(0)
	s_barrier
	v_mfma_f32_16x16x32_bf16 v[0:3], v[130:133], v[188:191], v[0:3]
	v_mfma_f32_16x16x32_bf16 v[4:7], v[152:155], v[188:191], v[4:7]
	v_mfma_f32_16x16x32_bf16 v[16:19], v[130:133], v[196:199], v[16:19]
	v_mfma_f32_16x16x32_bf16 v[20:23], v[152:155], v[196:199], v[20:23]
	v_mfma_f32_16x16x32_bf16 v[46:49], v[130:133], v[204:207], v[46:49]
	v_mfma_f32_16x16x32_bf16 v[50:53], v[152:155], v[204:207], v[50:53]
	v_mfma_f32_16x16x32_bf16 v[66:69], v[130:133], v[212:215], v[66:69]
	v_mfma_f32_16x16x32_bf16 v[70:73], v[152:155], v[212:215], v[70:73]
	v_mfma_f32_16x16x32_bf16 v[0:3], v[134:137], v[192:195], v[0:3]
	v_mfma_f32_16x16x32_bf16 v[4:7], v[156:159], v[192:195], v[4:7]
	v_mfma_f32_16x16x32_bf16 v[16:19], v[134:137], v[200:203], v[16:19]
	v_mfma_f32_16x16x32_bf16 v[20:23], v[156:159], v[200:203], v[20:23]
	v_mfma_f32_16x16x32_bf16 v[46:49], v[134:137], v[208:211], v[46:49]
	v_mfma_f32_16x16x32_bf16 v[50:53], v[156:159], v[208:211], v[50:53]
	v_mfma_f32_16x16x32_bf16 v[66:69], v[134:137], v[220:223], v[66:69]
	v_mfma_f32_16x16x32_bf16 v[70:73], v[156:159], v[220:223], v[70:73]
	v_mfma_f32_16x16x32_bf16 v[8:11], v[160:163], v[188:191], v[8:11]
	v_mfma_f32_16x16x32_bf16 v[12:15], v[180:183], v[188:191], v[12:15]
	v_mfma_f32_16x16x32_bf16 v[24:27], v[160:163], v[196:199], v[24:27]
	v_mfma_f32_16x16x32_bf16 v[28:31], v[180:183], v[196:199], v[28:31]
	v_mfma_f32_16x16x32_bf16 v[54:57], v[160:163], v[204:207], v[54:57]
	v_mfma_f32_16x16x32_bf16 v[58:61], v[180:183], v[204:207], v[58:61]
	v_mfma_f32_16x16x32_bf16 v[74:77], v[160:163], v[212:215], v[74:77]
	v_mfma_f32_16x16x32_bf16 v[78:81], v[180:183], v[212:215], v[78:81]
	v_mfma_f32_16x16x32_bf16 v[8:11], v[176:179], v[192:195], v[8:11]
	v_mfma_f32_16x16x32_bf16 v[12:15], v[184:187], v[192:195], v[12:15]
	v_mfma_f32_16x16x32_bf16 v[24:27], v[176:179], v[200:203], v[24:27]
	v_mfma_f32_16x16x32_bf16 v[28:31], v[184:187], v[200:203], v[28:31]
	v_mfma_f32_16x16x32_bf16 v[54:57], v[176:179], v[208:211], v[54:57]
	v_mfma_f32_16x16x32_bf16 v[58:61], v[184:187], v[208:211], v[58:61]
	v_mfma_f32_16x16x32_bf16 v[74:77], v[176:179], v[220:223], v[74:77]
	v_mfma_f32_16x16x32_bf16 v[78:81], v[184:187], v[220:223], v[78:81]
	s_barrier
	s_add_u32 s98, s24, s28
	s_addc_u32 s99, s25, s29
	s_add_u32 s100, s26, s28
	s_addc_u32 s101, s27, s29
	s_add_i32 s90, s90, s69
	s_add_i32 s91, s90, 0x2000
	s_mov_b32 m0, s90
	s_add_u32 s38, s24, 0x40000
	ds_read_b128 v[188:191], v170 offset:16384
	ds_read_b128 v[192:195], v170 offset:17408
	ds_read_b128 v[196:199], v170 offset:18432
	ds_read_b128 v[200:203], v170 offset:19456
	ds_read_b128 v[204:207], v170 offset:20480
	ds_read_b128 v[208:211], v170 offset:21504
	ds_read_b128 v[212:215], v170 offset:22528
	ds_read_b128 v[220:223], v170 offset:23552
	global_load_lds_dwordx4 v32, s[24:25]
	s_mov_b32 m0, s91
	s_addc_u32 s39, s25, 0
	s_add_i32 s33, s33, s69
	global_load_lds_dwordx4 v142, s[24:25]
	s_mov_b32 m0, s33
	s_nop 0
	global_load_lds_dwordx4 v32, s[38:39]
	s_add_i32 m0, s33, 0x2000
	s_nop 0
	global_load_lds_dwordx4 v142, s[38:39]
	s_add_i32 s38, s33, 0x2000
	s_mov_b32 m0, s77
	s_nop 0
	global_load_lds_dwordx4 v138, s[26:27]
	s_mov_b32 m0, s13
	s_nop 0
	global_load_lds_dwordx4 v140, s[26:27]
	s_waitcnt vmcnt(8)
	s_waitcnt lgkmcnt(0)
	s_barrier
	v_mfma_f32_16x16x32_bf16 v[82:85], v[130:133], v[188:191], v[82:85]
	v_mfma_f32_16x16x32_bf16 v[86:89], v[152:155], v[188:191], v[86:89]
	v_mfma_f32_16x16x32_bf16 v[106:109], v[130:133], v[196:199], v[106:109]
	v_mfma_f32_16x16x32_bf16 v[114:117], v[152:155], v[196:199], v[114:117]
	v_mfma_f32_16x16x32_bf16 v[126:129], v[130:133], v[204:207], v[126:129]
	v_mfma_f32_16x16x32_bf16 v[110:113], v[152:155], v[204:207], v[110:113]
	v_mfma_f32_16x16x32_bf16 v[62:65], v[130:133], v[212:215], v[62:65]
	v_mfma_f32_16x16x32_bf16 v[42:45], v[152:155], v[212:215], v[42:45]
	v_mfma_f32_16x16x32_bf16 v[82:85], v[134:137], v[192:195], v[82:85]
	v_mfma_f32_16x16x32_bf16 v[86:89], v[156:159], v[192:195], v[86:89]
	v_mfma_f32_16x16x32_bf16 v[106:109], v[134:137], v[200:203], v[106:109]
	v_mfma_f32_16x16x32_bf16 v[114:117], v[156:159], v[200:203], v[114:117]
	v_mfma_f32_16x16x32_bf16 v[126:129], v[134:137], v[208:211], v[126:129]
	v_mfma_f32_16x16x32_bf16 v[110:113], v[156:159], v[208:211], v[110:113]
	v_mfma_f32_16x16x32_bf16 v[62:65], v[134:137], v[220:223], v[62:65]
	v_mfma_f32_16x16x32_bf16 v[42:45], v[156:159], v[220:223], v[42:45]
	v_mfma_f32_16x16x32_bf16 v[90:93], v[160:163], v[188:191], v[90:93]
	v_mfma_f32_16x16x32_bf16 v[94:97], v[180:183], v[188:191], v[94:97]
	v_mfma_f32_16x16x32_bf16 v[118:121], v[160:163], v[196:199], v[118:121]
	v_mfma_f32_16x16x32_bf16 v[122:125], v[180:183], v[196:199], v[122:125]
	v_mfma_f32_16x16x32_bf16 v[102:105], v[160:163], v[204:207], v[102:105]
	v_mfma_f32_16x16x32_bf16 v[98:101], v[180:183], v[204:207], v[98:101]
	v_mfma_f32_16x16x32_bf16 v[38:41], v[160:163], v[212:215], v[38:41]
	v_mfma_f32_16x16x32_bf16 v[34:37], v[180:183], v[212:215], v[34:37]
	v_mfma_f32_16x16x32_bf16 v[90:93], v[176:179], v[192:195], v[90:93]
	v_mfma_f32_16x16x32_bf16 v[94:97], v[184:187], v[192:195], v[94:97]
	v_mfma_f32_16x16x32_bf16 v[118:121], v[176:179], v[200:203], v[118:121]
	v_mfma_f32_16x16x32_bf16 v[122:125], v[184:187], v[200:203], v[122:125]
	v_mfma_f32_16x16x32_bf16 v[102:105], v[176:179], v[208:211], v[102:105]
	v_mfma_f32_16x16x32_bf16 v[98:101], v[184:187], v[208:211], v[98:101]
	v_mfma_f32_16x16x32_bf16 v[38:41], v[176:179], v[220:223], v[38:41]
	v_mfma_f32_16x16x32_bf16 v[34:37], v[184:187], v[220:223], v[34:37]
	s_barrier
	s_add_i32 s39, 0, 0x18000
	s_add_i32 s65, 0, 0x1c000
	v_add_u32_e32 v176, s39, v169
	v_add_u32_e32 v177, s65, v169
	ds_read_b128 v[130:133], v176
	ds_read_b128 v[134:137], v176 offset:1024
	ds_read_b128 v[152:155], v176 offset:2048
	ds_read_b128 v[156:159], v176 offset:3072
	ds_read_b128 v[160:163], v177
	ds_read_b128 v[178:181], v177 offset:1024
	ds_read_b128 v[182:185], v177 offset:2048
	ds_read_b128 v[186:189], v177 offset:3072
	s_add_u32 s26, s26, 0x40000
	s_addc_u32 s27, s27, 0
	s_mov_b32 m0, s78
	ds_read_b128 v[190:193], v170 offset:32768
	ds_read_b128 v[194:197], v170 offset:33792
	ds_read_b128 v[198:201], v170 offset:34816
	ds_read_b128 v[202:205], v170 offset:35840
	ds_read_b128 v[206:209], v170 offset:36864
	ds_read_b128 v[210:213], v170 offset:37888
	ds_read_b128 v[220:223], v170 offset:38912
	ds_read_b128 v[224:227], v170 offset:39936
	global_load_lds_dwordx4 v138, s[26:27]
	s_mov_b32 m0, s12
	s_nop 0
	global_load_lds_dwordx4 v140, s[26:27]
	s_waitcnt vmcnt(8)
	s_waitcnt lgkmcnt(0)
	s_barrier
	v_mfma_f32_16x16x32_bf16 v[0:3], v[130:133], v[190:193], v[0:3]
	v_mfma_f32_16x16x32_bf16 v[4:7], v[152:155], v[190:193], v[4:7]
	v_mfma_f32_16x16x32_bf16 v[16:19], v[130:133], v[198:201], v[16:19]
	v_mfma_f32_16x16x32_bf16 v[20:23], v[152:155], v[198:201], v[20:23]
	v_mfma_f32_16x16x32_bf16 v[46:49], v[130:133], v[206:209], v[46:49]
	v_mfma_f32_16x16x32_bf16 v[50:53], v[152:155], v[206:209], v[50:53]
	v_mfma_f32_16x16x32_bf16 v[66:69], v[130:133], v[220:223], v[66:69]
	v_mfma_f32_16x16x32_bf16 v[70:73], v[152:155], v[220:223], v[70:73]
	v_mfma_f32_16x16x32_bf16 v[0:3], v[134:137], v[194:197], v[0:3]
	v_mfma_f32_16x16x32_bf16 v[4:7], v[156:159], v[194:197], v[4:7]
	v_mfma_f32_16x16x32_bf16 v[16:19], v[134:137], v[202:205], v[16:19]
	v_mfma_f32_16x16x32_bf16 v[20:23], v[156:159], v[202:205], v[20:23]
	v_mfma_f32_16x16x32_bf16 v[46:49], v[134:137], v[210:213], v[46:49]
	v_mfma_f32_16x16x32_bf16 v[50:53], v[156:159], v[210:213], v[50:53]
	v_mfma_f32_16x16x32_bf16 v[66:69], v[134:137], v[224:227], v[66:69]
	v_mfma_f32_16x16x32_bf16 v[70:73], v[156:159], v[224:227], v[70:73]
	v_mfma_f32_16x16x32_bf16 v[8:11], v[160:163], v[190:193], v[8:11]
	v_mfma_f32_16x16x32_bf16 v[12:15], v[182:185], v[190:193], v[12:15]
	v_mfma_f32_16x16x32_bf16 v[24:27], v[160:163], v[198:201], v[24:27]
	v_mfma_f32_16x16x32_bf16 v[28:31], v[182:185], v[198:201], v[28:31]
	v_mfma_f32_16x16x32_bf16 v[54:57], v[160:163], v[206:209], v[54:57]
	v_mfma_f32_16x16x32_bf16 v[58:61], v[182:185], v[206:209], v[58:61]
	v_mfma_f32_16x16x32_bf16 v[74:77], v[160:163], v[220:223], v[74:77]
	v_mfma_f32_16x16x32_bf16 v[78:81], v[182:185], v[220:223], v[78:81]
	v_mfma_f32_16x16x32_bf16 v[8:11], v[178:181], v[194:197], v[8:11]
	v_mfma_f32_16x16x32_bf16 v[12:15], v[186:189], v[194:197], v[12:15]
	v_mfma_f32_16x16x32_bf16 v[24:27], v[178:181], v[202:205], v[24:27]
	v_mfma_f32_16x16x32_bf16 v[28:31], v[186:189], v[202:205], v[28:31]
	v_mfma_f32_16x16x32_bf16 v[54:57], v[178:181], v[210:213], v[54:57]
	v_mfma_f32_16x16x32_bf16 v[58:61], v[186:189], v[210:213], v[58:61]
	v_mfma_f32_16x16x32_bf16 v[74:77], v[178:181], v[224:227], v[74:77]
	v_mfma_f32_16x16x32_bf16 v[78:81], v[186:189], v[224:227], v[78:81]
	s_barrier
	s_add_i32 s39, s39, s69
	s_add_i32 s64, s39, 0x2000
	s_mov_b32 m0, s39
	s_add_u32 s24, s24, 0x40080
	ds_read_b128 v[190:193], v170 offset:49152
	ds_read_b128 v[194:197], v170 offset:50176
	ds_read_b128 v[198:201], v170 offset:51200
	ds_read_b128 v[202:205], v170 offset:52224
	ds_read_b128 v[206:209], v170 offset:53248
	ds_read_b128 v[210:213], v170 offset:54272
	ds_read_b128 v[220:223], v170 offset:55296
	ds_read_b128 v[224:227], v170 offset:56320
	global_load_lds_dwordx4 v32, s[98:99]
	s_mov_b32 m0, s64
	s_addc_u32 s25, s25, 0
	s_add_i32 s65, s65, s69
	global_load_lds_dwordx4 v142, s[98:99]
	s_mov_b32 m0, s65
	s_add_i32 s0, s65, 0x2000
	global_load_lds_dwordx4 v32, s[24:25]
	s_mov_b32 m0, s0
	s_nop 0
	global_load_lds_dwordx4 v142, s[24:25]
	s_mov_b32 m0, s84
	s_nop 0
	global_load_lds_dwordx4 v138, s[100:101]
	s_mov_b32 m0, s85
	s_nop 0
	global_load_lds_dwordx4 v140, s[100:101]
	s_waitcnt vmcnt(8)
	s_waitcnt lgkmcnt(0)
	s_barrier
	v_mfma_f32_16x16x32_bf16 v[82:85], v[130:133], v[190:193], v[82:85]
	v_mfma_f32_16x16x32_bf16 v[86:89], v[152:155], v[190:193], v[86:89]
	v_mfma_f32_16x16x32_bf16 v[106:109], v[130:133], v[198:201], v[106:109]
	v_mfma_f32_16x16x32_bf16 v[114:117], v[152:155], v[198:201], v[114:117]
	v_mfma_f32_16x16x32_bf16 v[126:129], v[130:133], v[206:209], v[126:129]
	v_mfma_f32_16x16x32_bf16 v[110:113], v[152:155], v[206:209], v[110:113]
	v_mfma_f32_16x16x32_bf16 v[62:65], v[130:133], v[220:223], v[62:65]
	v_mfma_f32_16x16x32_bf16 v[42:45], v[152:155], v[220:223], v[42:45]
	v_mfma_f32_16x16x32_bf16 v[82:85], v[134:137], v[194:197], v[82:85]
	v_mfma_f32_16x16x32_bf16 v[86:89], v[156:159], v[194:197], v[86:89]
	v_mfma_f32_16x16x32_bf16 v[106:109], v[134:137], v[202:205], v[106:109]
	v_mfma_f32_16x16x32_bf16 v[114:117], v[156:159], v[202:205], v[114:117]
	v_mfma_f32_16x16x32_bf16 v[126:129], v[134:137], v[210:213], v[126:129]
	v_mfma_f32_16x16x32_bf16 v[110:113], v[156:159], v[210:213], v[110:113]
	v_mfma_f32_16x16x32_bf16 v[62:65], v[134:137], v[224:227], v[62:65]
	v_mfma_f32_16x16x32_bf16 v[42:45], v[156:159], v[224:227], v[42:45]
	v_mfma_f32_16x16x32_bf16 v[90:93], v[160:163], v[190:193], v[90:93]
	v_mfma_f32_16x16x32_bf16 v[94:97], v[182:185], v[190:193], v[94:97]
	v_mfma_f32_16x16x32_bf16 v[118:121], v[160:163], v[198:201], v[118:121]
	v_mfma_f32_16x16x32_bf16 v[122:125], v[182:185], v[198:201], v[122:125]
	v_mfma_f32_16x16x32_bf16 v[102:105], v[160:163], v[206:209], v[102:105]
	v_mfma_f32_16x16x32_bf16 v[98:101], v[182:185], v[206:209], v[98:101]
	v_mfma_f32_16x16x32_bf16 v[38:41], v[160:163], v[220:223], v[38:41]
	v_mfma_f32_16x16x32_bf16 v[34:37], v[182:185], v[220:223], v[34:37]
	v_mfma_f32_16x16x32_bf16 v[90:93], v[178:181], v[194:197], v[90:93]
	v_mfma_f32_16x16x32_bf16 v[94:97], v[186:189], v[194:197], v[94:97]
	v_mfma_f32_16x16x32_bf16 v[118:121], v[178:181], v[202:205], v[118:121]
	v_mfma_f32_16x16x32_bf16 v[122:125], v[186:189], v[202:205], v[122:125]
	v_mfma_f32_16x16x32_bf16 v[102:105], v[178:181], v[210:213], v[102:105]
	v_mfma_f32_16x16x32_bf16 v[98:101], v[186:189], v[210:213], v[98:101]
	v_mfma_f32_16x16x32_bf16 v[38:41], v[178:181], v[224:227], v[38:41]
	v_mfma_f32_16x16x32_bf16 v[34:37], v[186:189], v[224:227], v[34:37]
	s_barrier
	s_add_u32 s20, s20, 0x100
	s_addc_u32 s21, s21, 0
	s_add_u32 s22, s22, 0x100
	s_addc_u32 s23, s23, 0
	s_cmp_ge_i32 s42, s79
	s_mov_b32 s24, s42
	s_cbranch_scc0 .LBB0_381
	s_and_b64 vcc, exec, s[56:57]
	s_cbranch_vccz .LBB0_384
	s_barrier

.LBB0_405:
	ds_read_b128 v[134:137], v172
	ds_read_b128 v[152:155], v172 offset:1024
	ds_read_b128 v[156:159], v172 offset:2048
	ds_read_b128 v[160:163], v172 offset:3072
	ds_read_b128 v[178:181], v174
	ds_read_b128 v[182:185], v174 offset:1024
	ds_read_b128 v[186:189], v174 offset:2048
	ds_read_b128 v[190:193], v174 offset:3072
	s_add_u32 s26, s60, s24
	s_addc_u32 s27, s61, s25
	s_add_u32 s50, s62, s24
	s_addc_u32 s51, s63, s25
	s_cmp_eq_u32 s87, s49
	s_cselect_b32 s45, s1, s27
	s_cselect_b32 s44, s22, s26
	s_cselect_b32 s27, s23, s51
	s_cselect_b32 s26, s48, s50
	s_mov_b32 m0, s59
	ds_read_b128 v[194:197], v170
	ds_read_b128 v[198:201], v170 offset:1024
	ds_read_b128 v[202:205], v170 offset:2048
	ds_read_b128 v[206:209], v170 offset:3072
	ds_read_b128 v[210:213], v170 offset:4096
	ds_read_b128 v[220:223], v170 offset:5120
	ds_read_b128 v[224:227], v170 offset:6144
	ds_read_b128 v[228:231], v170 offset:7168
	global_load_lds_dwordx4 v132, s[60:61]
	s_mov_b32 m0, s89
	s_nop 0
	global_load_lds_dwordx4 v130, s[60:61]
	s_waitcnt vmcnt(8)
	s_waitcnt lgkmcnt(0)
	s_barrier
	v_mfma_f32_16x16x32_bf16 v[0:3], v[134:137], v[194:197], v[0:3]
	v_mfma_f32_16x16x32_bf16 v[4:7], v[156:159], v[194:197], v[4:7]
	v_mfma_f32_16x16x32_bf16 v[16:19], v[134:137], v[202:205], v[16:19]
	v_mfma_f32_16x16x32_bf16 v[20:23], v[156:159], v[202:205], v[20:23]
	v_mfma_f32_16x16x32_bf16 v[46:49], v[134:137], v[210:213], v[46:49]
	v_mfma_f32_16x16x32_bf16 v[50:53], v[156:159], v[210:213], v[50:53]
	v_mfma_f32_16x16x32_bf16 v[66:69], v[134:137], v[224:227], v[66:69]
	v_mfma_f32_16x16x32_bf16 v[70:73], v[156:159], v[224:227], v[70:73]
	v_mfma_f32_16x16x32_bf16 v[0:3], v[152:155], v[198:201], v[0:3]
	v_mfma_f32_16x16x32_bf16 v[4:7], v[160:163], v[198:201], v[4:7]
	v_mfma_f32_16x16x32_bf16 v[16:19], v[152:155], v[206:209], v[16:19]
	v_mfma_f32_16x16x32_bf16 v[20:23], v[160:163], v[206:209], v[20:23]
	v_mfma_f32_16x16x32_bf16 v[46:49], v[152:155], v[220:223], v[46:49]
	v_mfma_f32_16x16x32_bf16 v[50:53], v[160:163], v[220:223], v[50:53]
	v_mfma_f32_16x16x32_bf16 v[66:69], v[152:155], v[228:231], v[66:69]
	v_mfma_f32_16x16x32_bf16 v[70:73], v[160:163], v[228:231], v[70:73]
	v_mfma_f32_16x16x32_bf16 v[8:11], v[178:181], v[194:197], v[8:11]
	v_mfma_f32_16x16x32_bf16 v[12:15], v[186:189], v[194:197], v[12:15]
	v_mfma_f32_16x16x32_bf16 v[24:27], v[178:181], v[202:205], v[24:27]
	v_mfma_f32_16x16x32_bf16 v[28:31], v[186:189], v[202:205], v[28:31]
	v_mfma_f32_16x16x32_bf16 v[54:57], v[178:181], v[210:213], v[54:57]
	v_mfma_f32_16x16x32_bf16 v[58:61], v[186:189], v[210:213], v[58:61]
	v_mfma_f32_16x16x32_bf16 v[74:77], v[178:181], v[224:227], v[74:77]
	v_mfma_f32_16x16x32_bf16 v[78:81], v[186:189], v[224:227], v[78:81]
	v_mfma_f32_16x16x32_bf16 v[8:11], v[182:185], v[198:201], v[8:11]
	v_mfma_f32_16x16x32_bf16 v[12:15], v[190:193], v[198:201], v[12:15]
	v_mfma_f32_16x16x32_bf16 v[24:27], v[182:185], v[206:209], v[24:27]
	v_mfma_f32_16x16x32_bf16 v[28:31], v[190:193], v[206:209], v[28:31]
	v_mfma_f32_16x16x32_bf16 v[54:57], v[182:185], v[220:223], v[54:57]
	v_mfma_f32_16x16x32_bf16 v[58:61], v[190:193], v[220:223], v[58:61]
	v_mfma_f32_16x16x32_bf16 v[74:77], v[182:185], v[228:231], v[74:77]
	v_mfma_f32_16x16x32_bf16 v[78:81], v[190:193], v[228:231], v[78:81]
	s_barrier
	s_add_u32 s98, s26, s28
	s_addc_u32 s99, s27, s29
	s_add_u32 s100, s44, s28
	s_addc_u32 s101, s45, s29
	s_mov_b32 m0, s90
	s_add_u32 s50, s26, 0x40000
	ds_read_b128 v[194:197], v170 offset:16384
	ds_read_b128 v[198:201], v170 offset:17408
	ds_read_b128 v[202:205], v170 offset:18432
	ds_read_b128 v[206:209], v170 offset:19456
	ds_read_b128 v[210:213], v170 offset:20480
	ds_read_b128 v[220:223], v170 offset:21504
	ds_read_b128 v[224:227], v170 offset:22528
	ds_read_b128 v[228:231], v170 offset:23552
	global_load_lds_dwordx4 v32, s[26:27]
	s_mov_b32 m0, s91
	s_addc_u32 s51, s27, 0
	global_load_lds_dwordx4 v142, s[26:27]
	s_mov_b32 m0, s33
	s_nop 0
	global_load_lds_dwordx4 v32, s[50:51]
	s_mov_b32 m0, s38
	s_nop 0
	global_load_lds_dwordx4 v142, s[50:51]
	s_mov_b32 m0, s77
	s_nop 0
	global_load_lds_dwordx4 v138, s[44:45]
	s_mov_b32 m0, s13
	s_nop 0
	global_load_lds_dwordx4 v140, s[44:45]
	s_waitcnt vmcnt(8)
	s_waitcnt lgkmcnt(0)
	s_barrier
	v_mfma_f32_16x16x32_bf16 v[82:85], v[134:137], v[194:197], v[82:85]
	v_mfma_f32_16x16x32_bf16 v[86:89], v[156:159], v[194:197], v[86:89]
	v_mfma_f32_16x16x32_bf16 v[106:109], v[134:137], v[202:205], v[106:109]
	v_mfma_f32_16x16x32_bf16 v[114:117], v[156:159], v[202:205], v[114:117]
	v_mfma_f32_16x16x32_bf16 v[126:129], v[134:137], v[210:213], v[126:129]
	v_mfma_f32_16x16x32_bf16 v[110:113], v[156:159], v[210:213], v[110:113]
	v_mfma_f32_16x16x32_bf16 v[62:65], v[134:137], v[224:227], v[62:65]
	v_mfma_f32_16x16x32_bf16 v[42:45], v[156:159], v[224:227], v[42:45]
	v_mfma_f32_16x16x32_bf16 v[82:85], v[152:155], v[198:201], v[82:85]
	v_mfma_f32_16x16x32_bf16 v[86:89], v[160:163], v[198:201], v[86:89]
	v_mfma_f32_16x16x32_bf16 v[106:109], v[152:155], v[206:209], v[106:109]
	v_mfma_f32_16x16x32_bf16 v[114:117], v[160:163], v[206:209], v[114:117]
	v_mfma_f32_16x16x32_bf16 v[126:129], v[152:155], v[220:223], v[126:129]
	v_mfma_f32_16x16x32_bf16 v[110:113], v[160:163], v[220:223], v[110:113]
	v_mfma_f32_16x16x32_bf16 v[62:65], v[152:155], v[228:231], v[62:65]
	v_mfma_f32_16x16x32_bf16 v[42:45], v[160:163], v[228:231], v[42:45]
	v_mfma_f32_16x16x32_bf16 v[90:93], v[178:181], v[194:197], v[90:93]
	v_mfma_f32_16x16x32_bf16 v[94:97], v[186:189], v[194:197], v[94:97]
	v_mfma_f32_16x16x32_bf16 v[118:121], v[178:181], v[202:205], v[118:121]
	v_mfma_f32_16x16x32_bf16 v[122:125], v[186:189], v[202:205], v[122:125]
	v_mfma_f32_16x16x32_bf16 v[102:105], v[178:181], v[210:213], v[102:105]
	v_mfma_f32_16x16x32_bf16 v[98:101], v[186:189], v[210:213], v[98:101]
	v_mfma_f32_16x16x32_bf16 v[38:41], v[178:181], v[224:227], v[38:41]
	v_mfma_f32_16x16x32_bf16 v[34:37], v[186:189], v[224:227], v[34:37]
	v_mfma_f32_16x16x32_bf16 v[90:93], v[182:185], v[198:201], v[90:93]
	v_mfma_f32_16x16x32_bf16 v[94:97], v[190:193], v[198:201], v[94:97]
	v_mfma_f32_16x16x32_bf16 v[118:121], v[182:185], v[206:209], v[118:121]
	v_mfma_f32_16x16x32_bf16 v[122:125], v[190:193], v[206:209], v[122:125]
	v_mfma_f32_16x16x32_bf16 v[102:105], v[182:185], v[220:223], v[102:105]
	v_mfma_f32_16x16x32_bf16 v[98:101], v[190:193], v[220:223], v[98:101]
	v_mfma_f32_16x16x32_bf16 v[38:41], v[182:185], v[228:231], v[38:41]
	v_mfma_f32_16x16x32_bf16 v[34:37], v[190:193], v[228:231], v[34:37]
	s_barrier
	ds_read_b128 v[134:137], v176
	ds_read_b128 v[152:155], v176 offset:1024
	ds_read_b128 v[156:159], v176 offset:2048
	ds_read_b128 v[160:163], v176 offset:3072
	ds_read_b128 v[178:181], v177
	ds_read_b128 v[182:185], v177 offset:1024
	ds_read_b128 v[186:189], v177 offset:2048
	ds_read_b128 v[190:193], v177 offset:3072
	s_add_u32 s44, s44, 0x40000
	s_addc_u32 s45, s45, 0
	s_mov_b32 m0, s78
	ds_read_b128 v[194:197], v170 offset:32768
	ds_read_b128 v[198:201], v170 offset:33792
	ds_read_b128 v[202:205], v170 offset:34816
	ds_read_b128 v[206:209], v170 offset:35840
	ds_read_b128 v[210:213], v170 offset:36864
	ds_read_b128 v[220:223], v170 offset:37888
	ds_read_b128 v[224:227], v170 offset:38912
	ds_read_b128 v[228:231], v170 offset:39936
	global_load_lds_dwordx4 v138, s[44:45]
	s_mov_b32 m0, s12
	s_nop 0
	global_load_lds_dwordx4 v140, s[44:45]
	s_waitcnt vmcnt(8)
	s_waitcnt lgkmcnt(0)
	s_barrier
	v_mfma_f32_16x16x32_bf16 v[0:3], v[134:137], v[194:197], v[0:3]
	v_mfma_f32_16x16x32_bf16 v[4:7], v[156:159], v[194:197], v[4:7]
	v_mfma_f32_16x16x32_bf16 v[16:19], v[134:137], v[202:205], v[16:19]
	v_mfma_f32_16x16x32_bf16 v[20:23], v[156:159], v[202:205], v[20:23]
	v_mfma_f32_16x16x32_bf16 v[46:49], v[134:137], v[210:213], v[46:49]
	v_mfma_f32_16x16x32_bf16 v[50:53], v[156:159], v[210:213], v[50:53]
	v_mfma_f32_16x16x32_bf16 v[66:69], v[134:137], v[224:227], v[66:69]
	v_mfma_f32_16x16x32_bf16 v[70:73], v[156:159], v[224:227], v[70:73]
	v_mfma_f32_16x16x32_bf16 v[0:3], v[152:155], v[198:201], v[0:3]
	v_mfma_f32_16x16x32_bf16 v[4:7], v[160:163], v[198:201], v[4:7]
	v_mfma_f32_16x16x32_bf16 v[16:19], v[152:155], v[206:209], v[16:19]
	v_mfma_f32_16x16x32_bf16 v[20:23], v[160:163], v[206:209], v[20:23]
	v_mfma_f32_16x16x32_bf16 v[46:49], v[152:155], v[220:223], v[46:49]
	v_mfma_f32_16x16x32_bf16 v[50:53], v[160:163], v[220:223], v[50:53]
	v_mfma_f32_16x16x32_bf16 v[66:69], v[152:155], v[228:231], v[66:69]
	v_mfma_f32_16x16x32_bf16 v[70:73], v[160:163], v[228:231], v[70:73]
	v_mfma_f32_16x16x32_bf16 v[8:11], v[178:181], v[194:197], v[8:11]
	v_mfma_f32_16x16x32_bf16 v[12:15], v[186:189], v[194:197], v[12:15]
	v_mfma_f32_16x16x32_bf16 v[24:27], v[178:181], v[202:205], v[24:27]
	v_mfma_f32_16x16x32_bf16 v[28:31], v[186:189], v[202:205], v[28:31]
	v_mfma_f32_16x16x32_bf16 v[54:57], v[178:181], v[210:213], v[54:57]
	v_mfma_f32_16x16x32_bf16 v[58:61], v[186:189], v[210:213], v[58:61]
	v_mfma_f32_16x16x32_bf16 v[74:77], v[178:181], v[224:227], v[74:77]
	v_mfma_f32_16x16x32_bf16 v[78:81], v[186:189], v[224:227], v[78:81]
	v_mfma_f32_16x16x32_bf16 v[8:11], v[182:185], v[198:201], v[8:11]
	v_mfma_f32_16x16x32_bf16 v[12:15], v[190:193], v[198:201], v[12:15]
	v_mfma_f32_16x16x32_bf16 v[24:27], v[182:185], v[206:209], v[24:27]
	v_mfma_f32_16x16x32_bf16 v[28:31], v[190:193], v[206:209], v[28:31]
	v_mfma_f32_16x16x32_bf16 v[54:57], v[182:185], v[220:223], v[54:57]
	v_mfma_f32_16x16x32_bf16 v[58:61], v[190:193], v[220:223], v[58:61]
	v_mfma_f32_16x16x32_bf16 v[74:77], v[182:185], v[228:231], v[74:77]
	v_mfma_f32_16x16x32_bf16 v[78:81], v[190:193], v[228:231], v[78:81]
	s_barrier
	s_mov_b32 m0, s39
	s_add_u32 s26, s26, 0x40080
	ds_read_b128 v[194:197], v170 offset:49152
	ds_read_b128 v[198:201], v170 offset:50176
	ds_read_b128 v[202:205], v170 offset:51200
	ds_read_b128 v[206:209], v170 offset:52224
	ds_read_b128 v[210:213], v170 offset:53248
	ds_read_b128 v[220:223], v170 offset:54272
	ds_read_b128 v[224:227], v170 offset:55296
	ds_read_b128 v[228:231], v170 offset:56320
	global_load_lds_dwordx4 v32, s[98:99]
	s_mov_b32 m0, s64
	s_addc_u32 s27, s27, 0
	global_load_lds_dwordx4 v142, s[98:99]
	s_mov_b32 m0, s65
	s_nop 0
	global_load_lds_dwordx4 v32, s[26:27]
	s_mov_b32 m0, s0
	s_nop 0
	global_load_lds_dwordx4 v142, s[26:27]
	s_mov_b32 m0, s84
	s_nop 0
	global_load_lds_dwordx4 v138, s[100:101]
	s_mov_b32 m0, s85
	s_nop 0
	global_load_lds_dwordx4 v140, s[100:101]
	s_waitcnt vmcnt(8)
	s_waitcnt lgkmcnt(0)
	s_barrier
	v_mfma_f32_16x16x32_bf16 v[82:85], v[134:137], v[194:197], v[82:85]
	v_mfma_f32_16x16x32_bf16 v[86:89], v[156:159], v[194:197], v[86:89]
	v_mfma_f32_16x16x32_bf16 v[106:109], v[134:137], v[202:205], v[106:109]
	v_mfma_f32_16x16x32_bf16 v[114:117], v[156:159], v[202:205], v[114:117]
	v_mfma_f32_16x16x32_bf16 v[126:129], v[134:137], v[210:213], v[126:129]
	v_mfma_f32_16x16x32_bf16 v[110:113], v[156:159], v[210:213], v[110:113]
	v_mfma_f32_16x16x32_bf16 v[62:65], v[134:137], v[224:227], v[62:65]
	v_mfma_f32_16x16x32_bf16 v[42:45], v[156:159], v[224:227], v[42:45]
	v_mfma_f32_16x16x32_bf16 v[82:85], v[152:155], v[198:201], v[82:85]
	v_mfma_f32_16x16x32_bf16 v[86:89], v[160:163], v[198:201], v[86:89]
	v_mfma_f32_16x16x32_bf16 v[106:109], v[152:155], v[206:209], v[106:109]
	v_mfma_f32_16x16x32_bf16 v[114:117], v[160:163], v[206:209], v[114:117]
	v_mfma_f32_16x16x32_bf16 v[126:129], v[152:155], v[220:223], v[126:129]
	v_mfma_f32_16x16x32_bf16 v[110:113], v[160:163], v[220:223], v[110:113]
	v_mfma_f32_16x16x32_bf16 v[62:65], v[152:155], v[228:231], v[62:65]
	v_mfma_f32_16x16x32_bf16 v[42:45], v[160:163], v[228:231], v[42:45]
	v_mfma_f32_16x16x32_bf16 v[90:93], v[178:181], v[194:197], v[90:93]
	v_mfma_f32_16x16x32_bf16 v[94:97], v[186:189], v[194:197], v[94:97]
	v_mfma_f32_16x16x32_bf16 v[118:121], v[178:181], v[202:205], v[118:121]
	v_mfma_f32_16x16x32_bf16 v[122:125], v[186:189], v[202:205], v[122:125]
	v_mfma_f32_16x16x32_bf16 v[102:105], v[178:181], v[210:213], v[102:105]
	v_mfma_f32_16x16x32_bf16 v[98:101], v[186:189], v[210:213], v[98:101]
	v_mfma_f32_16x16x32_bf16 v[38:41], v[178:181], v[224:227], v[38:41]
	v_mfma_f32_16x16x32_bf16 v[34:37], v[186:189], v[224:227], v[34:37]
	v_mfma_f32_16x16x32_bf16 v[90:93], v[182:185], v[198:201], v[90:93]
	v_mfma_f32_16x16x32_bf16 v[94:97], v[190:193], v[198:201], v[94:97]
	v_mfma_f32_16x16x32_bf16 v[118:121], v[182:185], v[206:209], v[118:121]
	v_mfma_f32_16x16x32_bf16 v[122:125], v[190:193], v[206:209], v[122:125]
	v_mfma_f32_16x16x32_bf16 v[102:105], v[182:185], v[220:223], v[102:105]
	v_mfma_f32_16x16x32_bf16 v[98:101], v[190:193], v[220:223], v[98:101]
	v_mfma_f32_16x16x32_bf16 v[38:41], v[182:185], v[228:231], v[38:41]
	v_mfma_f32_16x16x32_bf16 v[34:37], v[190:193], v[228:231], v[34:37]
	s_barrier
	s_add_i32 s26, s49, 2
	s_add_u32 s24, s24, 0x100
	s_addc_u32 s25, s25, 0
	v_lshl_add_u64 v[132:133], v[132:133], 0, s[30:31]
	v_lshl_add_u64 v[130:131], v[130:131], 0, s[30:31]
	s_cmp_ge_i32 s49, s87
	s_mov_b32 s49, s26
	s_cbranch_scc0 .LBB0_405
	s_and_b64 vcc, exec, s[56:57]
	s_cbranch_vccz .LBB0_408
	s_barrier

.LBB0_584:
	s_add_u32 s47, s56, 0xfffc0080
	s_addc_u32 s58, s57, -1
	s_add_i32 s65, 0, 0x10000
	s_cmp_eq_u32 s45, 12
	s_cselect_b32 s61, s53, s58
	s_cselect_b32 s60, s52, s47
	s_cselect_b32 s59, s55, s19
	s_cselect_b32 s58, s54, s18
	s_add_i32 s47, 0, 0x14000
	v_add_u32_e32 v152, s65, v157
	v_add_u32_e32 v159, s47, v157
	ds_read_b128 v[130:133], v152
	ds_read_b128 v[144:147], v152 offset:1024
	ds_read_b128 v[148:151], v152 offset:2048
	ds_read_b128 v[152:155], v152 offset:3072
	ds_read_b128 v[176:179], v159
	ds_read_b128 v[180:183], v159 offset:1024
	ds_read_b128 v[184:187], v159 offset:2048
	ds_read_b128 v[188:191], v159 offset:3072
	s_add_i32 m0, s1, 0xc000
	ds_read_b128 v[192:195], v158
	ds_read_b128 v[196:199], v158 offset:1024
	ds_read_b128 v[200:203], v158 offset:2048
	ds_read_b128 v[204:207], v158 offset:3072
	ds_read_b128 v[208:211], v158 offset:4096
	ds_read_b128 v[212:215], v158 offset:5120
	ds_read_b128 v[224:227], v158 offset:6144
	ds_read_b128 v[228:231], v158 offset:7168
	global_load_lds_dwordx4 v140, s[56:57]
	s_add_i32 m0, s1, 0xe000
	s_nop 0
	global_load_lds_dwordx4 v142, s[56:57]
	s_waitcnt vmcnt(8)
	s_waitcnt lgkmcnt(0)
	s_barrier
	v_mfma_f32_16x16x32_bf16 v[126:129], v[130:133], v[192:195], v[126:129]
	v_mfma_f32_16x16x32_bf16 v[122:125], v[148:151], v[192:195], v[122:125]
	v_mfma_f32_16x16x32_bf16 v[118:121], v[130:133], v[200:203], v[118:121]
	v_mfma_f32_16x16x32_bf16 v[110:113], v[148:151], v[200:203], v[110:113]
	v_mfma_f32_16x16x32_bf16 v[102:105], v[130:133], v[208:211], v[102:105]
	v_mfma_f32_16x16x32_bf16 v[94:97], v[148:151], v[208:211], v[94:97]
	v_mfma_f32_16x16x32_bf16 v[86:89], v[130:133], v[224:227], v[86:89]
	v_mfma_f32_16x16x32_bf16 v[78:81], v[148:151], v[224:227], v[78:81]
	v_mfma_f32_16x16x32_bf16 v[126:129], v[144:147], v[196:199], v[126:129]
	v_mfma_f32_16x16x32_bf16 v[122:125], v[152:155], v[196:199], v[122:125]
	v_mfma_f32_16x16x32_bf16 v[118:121], v[144:147], v[204:207], v[118:121]
	v_mfma_f32_16x16x32_bf16 v[110:113], v[152:155], v[204:207], v[110:113]
	v_mfma_f32_16x16x32_bf16 v[102:105], v[144:147], v[212:215], v[102:105]
	v_mfma_f32_16x16x32_bf16 v[94:97], v[152:155], v[212:215], v[94:97]
	v_mfma_f32_16x16x32_bf16 v[86:89], v[144:147], v[228:231], v[86:89]
	v_mfma_f32_16x16x32_bf16 v[78:81], v[152:155], v[228:231], v[78:81]
	v_mfma_f32_16x16x32_bf16 v[114:117], v[176:179], v[192:195], v[114:117]
	v_mfma_f32_16x16x32_bf16 v[106:109], v[184:187], v[192:195], v[106:109]
	v_mfma_f32_16x16x32_bf16 v[98:101], v[176:179], v[200:203], v[98:101]
	v_mfma_f32_16x16x32_bf16 v[90:93], v[184:187], v[200:203], v[90:93]
	v_mfma_f32_16x16x32_bf16 v[82:85], v[176:179], v[208:211], v[82:85]
	v_mfma_f32_16x16x32_bf16 v[74:77], v[184:187], v[208:211], v[74:77]
	v_mfma_f32_16x16x32_bf16 v[70:73], v[176:179], v[224:227], v[70:73]
	v_mfma_f32_16x16x32_bf16 v[66:69], v[184:187], v[224:227], v[66:69]
	v_mfma_f32_16x16x32_bf16 v[114:117], v[180:183], v[196:199], v[114:117]
	v_mfma_f32_16x16x32_bf16 v[106:109], v[188:191], v[196:199], v[106:109]
	v_mfma_f32_16x16x32_bf16 v[98:101], v[180:183], v[204:207], v[98:101]
	v_mfma_f32_16x16x32_bf16 v[90:93], v[188:191], v[204:207], v[90:93]
	v_mfma_f32_16x16x32_bf16 v[82:85], v[180:183], v[212:215], v[82:85]
	v_mfma_f32_16x16x32_bf16 v[74:77], v[188:191], v[212:215], v[74:77]
	v_mfma_f32_16x16x32_bf16 v[70:73], v[180:183], v[228:231], v[70:73]
	v_mfma_f32_16x16x32_bf16 v[66:69], v[188:191], v[228:231], v[66:69]
	s_barrier
	s_add_u32 s98, s58, s28
	s_addc_u32 s99, s59, s29
	s_add_u32 s100, s60, s28
	s_addc_u32 s101, s61, s29
	s_add_i32 s65, s65, s0
	s_mov_b32 m0, s65
	ds_read_b128 v[192:195], v158 offset:16384
	ds_read_b128 v[196:199], v158 offset:17408
	ds_read_b128 v[200:203], v158 offset:18432
	ds_read_b128 v[204:207], v158 offset:19456
	ds_read_b128 v[208:211], v158 offset:20480
	ds_read_b128 v[212:215], v158 offset:21504
	ds_read_b128 v[224:227], v158 offset:22528
	ds_read_b128 v[228:231], v158 offset:23552
	global_load_lds_dwordx4 v32, s[58:59]
	s_add_i32 m0, s65, 0x2000
	s_add_u32 s66, s58, 0x40000
	s_addc_u32 s67, s59, 0
	s_add_i32 s47, s47, s0
	global_load_lds_dwordx4 v134, s[58:59]
	s_mov_b32 m0, s47
	s_nop 0
	global_load_lds_dwordx4 v32, s[66:67]
	s_add_i32 m0, s47, 0x2000
	s_nop 0
	global_load_lds_dwordx4 v134, s[66:67]
	s_mov_b32 m0, s1
	s_nop 0
	global_load_lds_dwordx4 v138, s[60:61]
	s_mov_b32 m0, s4
	s_nop 0
	global_load_lds_dwordx4 v136, s[60:61]
	s_waitcnt vmcnt(8)
	s_waitcnt lgkmcnt(0)
	s_barrier
	v_mfma_f32_16x16x32_bf16 v[62:65], v[130:133], v[192:195], v[62:65]
	v_mfma_f32_16x16x32_bf16 v[58:61], v[148:151], v[192:195], v[58:61]
	v_mfma_f32_16x16x32_bf16 v[54:57], v[130:133], v[200:203], v[54:57]
	v_mfma_f32_16x16x32_bf16 v[46:49], v[148:151], v[200:203], v[46:49]
	v_mfma_f32_16x16x32_bf16 v[38:41], v[130:133], v[208:211], v[38:41]
	v_mfma_f32_16x16x32_bf16 v[28:31], v[148:151], v[208:211], v[28:31]
	v_mfma_f32_16x16x32_bf16 v[20:23], v[130:133], v[224:227], v[20:23]
	v_mfma_f32_16x16x32_bf16 v[12:15], v[148:151], v[224:227], v[12:15]
	v_mfma_f32_16x16x32_bf16 v[62:65], v[144:147], v[196:199], v[62:65]
	v_mfma_f32_16x16x32_bf16 v[58:61], v[152:155], v[196:199], v[58:61]
	v_mfma_f32_16x16x32_bf16 v[54:57], v[144:147], v[204:207], v[54:57]
	v_mfma_f32_16x16x32_bf16 v[46:49], v[152:155], v[204:207], v[46:49]
	v_mfma_f32_16x16x32_bf16 v[38:41], v[144:147], v[212:215], v[38:41]
	v_mfma_f32_16x16x32_bf16 v[28:31], v[152:155], v[212:215], v[28:31]
	v_mfma_f32_16x16x32_bf16 v[20:23], v[144:147], v[228:231], v[20:23]
	v_mfma_f32_16x16x32_bf16 v[12:15], v[152:155], v[228:231], v[12:15]
	v_mfma_f32_16x16x32_bf16 v[50:53], v[176:179], v[192:195], v[50:53]
	v_mfma_f32_16x16x32_bf16 v[42:45], v[184:187], v[192:195], v[42:45]
	v_mfma_f32_16x16x32_bf16 v[34:37], v[176:179], v[200:203], v[34:37]
	v_mfma_f32_16x16x32_bf16 v[24:27], v[184:187], v[200:203], v[24:27]
	v_mfma_f32_16x16x32_bf16 v[16:19], v[176:179], v[208:211], v[16:19]
	v_mfma_f32_16x16x32_bf16 v[8:11], v[184:187], v[208:211], v[8:11]
	v_mfma_f32_16x16x32_bf16 v[4:7], v[176:179], v[224:227], v[4:7]
	v_mfma_f32_16x16x32_bf16 v[0:3], v[184:187], v[224:227], v[0:3]
	v_mfma_f32_16x16x32_bf16 v[50:53], v[180:183], v[196:199], v[50:53]
	v_mfma_f32_16x16x32_bf16 v[42:45], v[188:191], v[196:199], v[42:45]
	v_mfma_f32_16x16x32_bf16 v[34:37], v[180:183], v[204:207], v[34:37]
	v_mfma_f32_16x16x32_bf16 v[24:27], v[188:191], v[204:207], v[24:27]
	v_mfma_f32_16x16x32_bf16 v[16:19], v[180:183], v[212:215], v[16:19]
	v_mfma_f32_16x16x32_bf16 v[8:11], v[188:191], v[212:215], v[8:11]
	v_mfma_f32_16x16x32_bf16 v[4:7], v[180:183], v[228:231], v[4:7]
	v_mfma_f32_16x16x32_bf16 v[0:3], v[188:191], v[228:231], v[0:3]
	s_barrier
	s_add_i32 s47, 0, 0x18000
	s_add_i32 s65, 0, 0x1c000
	v_add_u32_e32 v152, s47, v157
	v_add_u32_e32 v159, s65, v157
	ds_read_b128 v[130:133], v152
	ds_read_b128 v[144:147], v152 offset:1024
	ds_read_b128 v[148:151], v152 offset:2048
	ds_read_b128 v[152:155], v152 offset:3072
	ds_read_b128 v[176:179], v159
	ds_read_b128 v[180:183], v159 offset:1024
	ds_read_b128 v[184:187], v159 offset:2048
	ds_read_b128 v[188:191], v159 offset:3072
	s_add_u32 s60, s60, 0x40000
	s_addc_u32 s61, s61, 0
	s_mov_b32 m0, s5
	ds_read_b128 v[192:195], v158 offset:32768
	ds_read_b128 v[196:199], v158 offset:33792
	ds_read_b128 v[200:203], v158 offset:34816
	ds_read_b128 v[204:207], v158 offset:35840
	ds_read_b128 v[208:211], v158 offset:36864
	ds_read_b128 v[212:215], v158 offset:37888
	ds_read_b128 v[224:227], v158 offset:38912
	ds_read_b128 v[228:231], v158 offset:39936
	global_load_lds_dwordx4 v138, s[60:61]
	s_mov_b32 m0, s8
	s_nop 0
	global_load_lds_dwordx4 v136, s[60:61]
	s_waitcnt vmcnt(8)
	s_waitcnt lgkmcnt(0)
	s_barrier
	v_mfma_f32_16x16x32_bf16 v[126:129], v[130:133], v[192:195], v[126:129]
	v_mfma_f32_16x16x32_bf16 v[122:125], v[148:151], v[192:195], v[122:125]
	v_mfma_f32_16x16x32_bf16 v[118:121], v[130:133], v[200:203], v[118:121]
	v_mfma_f32_16x16x32_bf16 v[110:113], v[148:151], v[200:203], v[110:113]
	v_mfma_f32_16x16x32_bf16 v[102:105], v[130:133], v[208:211], v[102:105]
	v_mfma_f32_16x16x32_bf16 v[94:97], v[148:151], v[208:211], v[94:97]
	v_mfma_f32_16x16x32_bf16 v[86:89], v[130:133], v[224:227], v[86:89]
	v_mfma_f32_16x16x32_bf16 v[78:81], v[148:151], v[224:227], v[78:81]
	v_mfma_f32_16x16x32_bf16 v[126:129], v[144:147], v[196:199], v[126:129]
	v_mfma_f32_16x16x32_bf16 v[122:125], v[152:155], v[196:199], v[122:125]
	v_mfma_f32_16x16x32_bf16 v[118:121], v[144:147], v[204:207], v[118:121]
	v_mfma_f32_16x16x32_bf16 v[110:113], v[152:155], v[204:207], v[110:113]
	v_mfma_f32_16x16x32_bf16 v[102:105], v[144:147], v[212:215], v[102:105]
	v_mfma_f32_16x16x32_bf16 v[94:97], v[152:155], v[212:215], v[94:97]
	v_mfma_f32_16x16x32_bf16 v[86:89], v[144:147], v[228:231], v[86:89]
	v_mfma_f32_16x16x32_bf16 v[78:81], v[152:155], v[228:231], v[78:81]
	v_mfma_f32_16x16x32_bf16 v[114:117], v[176:179], v[192:195], v[114:117]
	v_mfma_f32_16x16x32_bf16 v[106:109], v[184:187], v[192:195], v[106:109]
	v_mfma_f32_16x16x32_bf16 v[98:101], v[176:179], v[200:203], v[98:101]
	v_mfma_f32_16x16x32_bf16 v[90:93], v[184:187], v[200:203], v[90:93]
	v_mfma_f32_16x16x32_bf16 v[82:85], v[176:179], v[208:211], v[82:85]
	v_mfma_f32_16x16x32_bf16 v[74:77], v[184:187], v[208:211], v[74:77]
	v_mfma_f32_16x16x32_bf16 v[70:73], v[176:179], v[224:227], v[70:73]
	v_mfma_f32_16x16x32_bf16 v[66:69], v[184:187], v[224:227], v[66:69]
	v_mfma_f32_16x16x32_bf16 v[114:117], v[180:183], v[196:199], v[114:117]
	v_mfma_f32_16x16x32_bf16 v[106:109], v[188:191], v[196:199], v[106:109]
	v_mfma_f32_16x16x32_bf16 v[98:101], v[180:183], v[204:207], v[98:101]
	v_mfma_f32_16x16x32_bf16 v[90:93], v[188:191], v[204:207], v[90:93]
	v_mfma_f32_16x16x32_bf16 v[82:85], v[180:183], v[212:215], v[82:85]
	v_mfma_f32_16x16x32_bf16 v[74:77], v[188:191], v[212:215], v[74:77]
	v_mfma_f32_16x16x32_bf16 v[70:73], v[180:183], v[228:231], v[70:73]
	v_mfma_f32_16x16x32_bf16 v[66:69], v[188:191], v[228:231], v[66:69]
	s_barrier
	s_add_i32 s47, s47, s0
	s_mov_b32 m0, s47
	ds_read_b128 v[192:195], v158 offset:49152
	ds_read_b128 v[196:199], v158 offset:50176
	ds_read_b128 v[200:203], v158 offset:51200
	ds_read_b128 v[204:207], v158 offset:52224
	ds_read_b128 v[208:211], v158 offset:53248
	ds_read_b128 v[212:215], v158 offset:54272
	ds_read_b128 v[224:227], v158 offset:55296
	ds_read_b128 v[228:231], v158 offset:56320
	global_load_lds_dwordx4 v32, s[98:99]
	s_add_i32 m0, s47, 0x2000
	s_add_u32 s58, s58, 0x40080
	s_addc_u32 s59, s59, 0
	s_add_i32 s47, s65, s0
	global_load_lds_dwordx4 v134, s[98:99]
	s_mov_b32 m0, s47
	s_nop 0
	global_load_lds_dwordx4 v32, s[58:59]
	s_add_i32 m0, s47, 0x2000
	s_nop 0
	global_load_lds_dwordx4 v134, s[58:59]
	s_mov_b32 m0, s33
	s_nop 0
	global_load_lds_dwordx4 v138, s[100:101]
	s_mov_b32 m0, s38
	s_nop 0
	global_load_lds_dwordx4 v136, s[100:101]
	s_waitcnt vmcnt(8)
	s_waitcnt lgkmcnt(0)
	s_barrier
	v_mfma_f32_16x16x32_bf16 v[62:65], v[130:133], v[192:195], v[62:65]
	v_mfma_f32_16x16x32_bf16 v[58:61], v[148:151], v[192:195], v[58:61]
	v_mfma_f32_16x16x32_bf16 v[54:57], v[130:133], v[200:203], v[54:57]
	v_mfma_f32_16x16x32_bf16 v[46:49], v[148:151], v[200:203], v[46:49]
	v_mfma_f32_16x16x32_bf16 v[38:41], v[130:133], v[208:211], v[38:41]
	v_mfma_f32_16x16x32_bf16 v[28:31], v[148:151], v[208:211], v[28:31]
	v_mfma_f32_16x16x32_bf16 v[20:23], v[130:133], v[224:227], v[20:23]
	v_mfma_f32_16x16x32_bf16 v[12:15], v[148:151], v[224:227], v[12:15]
	v_mfma_f32_16x16x32_bf16 v[62:65], v[144:147], v[196:199], v[62:65]
	v_mfma_f32_16x16x32_bf16 v[58:61], v[152:155], v[196:199], v[58:61]
	v_mfma_f32_16x16x32_bf16 v[54:57], v[144:147], v[204:207], v[54:57]
	v_mfma_f32_16x16x32_bf16 v[46:49], v[152:155], v[204:207], v[46:49]
	v_mfma_f32_16x16x32_bf16 v[38:41], v[144:147], v[212:215], v[38:41]
	v_mfma_f32_16x16x32_bf16 v[28:31], v[152:155], v[212:215], v[28:31]
	v_mfma_f32_16x16x32_bf16 v[20:23], v[144:147], v[228:231], v[20:23]
	v_mfma_f32_16x16x32_bf16 v[12:15], v[152:155], v[228:231], v[12:15]
	v_mfma_f32_16x16x32_bf16 v[50:53], v[176:179], v[192:195], v[50:53]
	v_mfma_f32_16x16x32_bf16 v[42:45], v[184:187], v[192:195], v[42:45]
	v_mfma_f32_16x16x32_bf16 v[34:37], v[176:179], v[200:203], v[34:37]
	v_mfma_f32_16x16x32_bf16 v[24:27], v[184:187], v[200:203], v[24:27]
	v_mfma_f32_16x16x32_bf16 v[16:19], v[176:179], v[208:211], v[16:19]
	v_mfma_f32_16x16x32_bf16 v[8:11], v[184:187], v[208:211], v[8:11]
	v_mfma_f32_16x16x32_bf16 v[4:7], v[176:179], v[224:227], v[4:7]
	v_mfma_f32_16x16x32_bf16 v[0:3], v[184:187], v[224:227], v[0:3]
	v_mfma_f32_16x16x32_bf16 v[50:53], v[180:183], v[196:199], v[50:53]
	v_mfma_f32_16x16x32_bf16 v[42:45], v[188:191], v[196:199], v[42:45]
	v_mfma_f32_16x16x32_bf16 v[34:37], v[180:183], v[204:207], v[34:37]
	v_mfma_f32_16x16x32_bf16 v[24:27], v[188:191], v[204:207], v[24:27]
	v_mfma_f32_16x16x32_bf16 v[16:19], v[180:183], v[212:215], v[16:19]
	v_mfma_f32_16x16x32_bf16 v[8:11], v[188:191], v[212:215], v[8:11]
	v_mfma_f32_16x16x32_bf16 v[4:7], v[180:183], v[228:231], v[4:7]
	v_mfma_f32_16x16x32_bf16 v[0:3], v[188:191], v[228:231], v[0:3]
	s_barrier
	s_add_i32 s45, s45, 2
	s_add_u32 s56, s56, 0x100
	s_addc_u32 s57, s57, 0
	s_add_u32 s18, s18, 0x100
	s_addc_u32 s19, s19, 0
	s_cmp_gt_u32 s45, 13
	s_cbranch_scc0 .LBB0_584
	s_and_b64 vcc, exec, s[24:25]
	s_cbranch_vccz .LBB0_587
	s_barrier
